# GEMM tiles: first K-pair peeled, first MFMA of each accumulator takes C=0; the 128 accumulator-zeroing v_mov per tile removed
# speedup vs baseline: 1.0090x; 1.0079x over previous
.LBB0_151:
	s_ashr_i32 s37, s36, 31
	s_lshl_b64 s[38:39], s[36:37], 19
	s_add_u32 s38, s74, s38
	s_addc_u32 s39, s75, s39
	s_and_b64 s[40:41], s[6:7], exec
	s_cselect_b32 s11, s39, s71
	s_cselect_b32 s22, s38, s70
	s_ashr_i32 s35, s34, 31
	s_lshl_b64 s[40:41], s[34:35], 19
	s_add_u32 s40, s20, s40
	s_addc_u32 s41, s21, s41
	s_and_b64 s[80:81], s[6:7], exec
	s_cselect_b32 s35, s41, s79
	s_cselect_b32 s37, s40, s78
	s_add_u32 s70, s70, 0x40080
	s_addc_u32 s71, s71, 0
	s_add_u32 s94, s78, 0x100
	s_addc_u32 s95, s79, 0
	s_mov_b32 s96, -2
	s_waitcnt lgkmcnt(0)
	ds_read_b128 v[128:131], v192
	ds_read_b128 v[132:135], v192 offset:1024
	ds_read_b128 v[136:139], v192 offset:2048
	ds_read_b128 v[140:143], v192 offset:3072
	ds_read_b128 v[164:167], v193
	ds_read_b128 v[168:171], v193 offset:1024
	ds_read_b128 v[172:175], v193 offset:2048
	ds_read_b128 v[176:179], v193 offset:3072
	s_add_u32 s78, s70, 0xfffc0080
	s_addc_u32 s79, s71, -1
	s_cmp_eq_u32 s96, 12
	s_cselect_b32 s81, s11, s79
	s_cselect_b32 s80, s22, s78
	s_cselect_b32 s79, s35, s95
	s_cselect_b32 s78, s37, s94
	v_lshl_add_u64 v[228:229], s[70:71], 0, v[156:157]
	s_add_i32 m0, s82, 0xc000
	ds_read_b128 v[196:199], v194
	ds_read_b128 v[200:203], v194 offset:1024
	ds_read_b128 v[204:207], v194 offset:2048
	ds_read_b128 v[208:211], v194 offset:3072
	ds_read_b128 v[212:215], v194 offset:4096
	ds_read_b128 v[216:219], v194 offset:5120
	ds_read_b128 v[220:223], v194 offset:6144
	ds_read_b128 v[224:227], v194 offset:7168
	global_load_lds_dwordx4 v[228:229], off
	v_lshl_add_u64 v[228:229], s[70:71], 0, v[158:159]
	s_add_i32 m0, s82, 0xe000
	s_nop 0
	global_load_lds_dwordx4 v[228:229], off
	s_waitcnt vmcnt(8)
	s_waitcnt lgkmcnt(0)
	s_barrier
	s_waitcnt lgkmcnt(0)
	v_mfma_f32_16x16x32_bf16 v[124:127], v[128:131], v[196:199], 0
	v_mfma_f32_16x16x32_bf16 v[120:123], v[136:139], v[196:199], 0
	v_mfma_f32_16x16x32_bf16 v[108:111], v[128:131], v[204:207], 0
	v_mfma_f32_16x16x32_bf16 v[104:107], v[136:139], v[204:207], 0
	v_mfma_f32_16x16x32_bf16 v[92:95], v[128:131], v[212:215], 0
	v_mfma_f32_16x16x32_bf16 v[88:91], v[136:139], v[212:215], 0
	v_mfma_f32_16x16x32_bf16 v[76:79], v[128:131], v[220:223], 0
	v_mfma_f32_16x16x32_bf16 v[72:75], v[136:139], v[220:223], 0
	v_mfma_f32_16x16x32_bf16 v[124:127], v[132:135], v[200:203], v[124:127]
	v_mfma_f32_16x16x32_bf16 v[120:123], v[140:143], v[200:203], v[120:123]
	v_mfma_f32_16x16x32_bf16 v[108:111], v[132:135], v[208:211], v[108:111]
	v_mfma_f32_16x16x32_bf16 v[104:107], v[140:143], v[208:211], v[104:107]
	v_mfma_f32_16x16x32_bf16 v[92:95], v[132:135], v[216:219], v[92:95]
	v_mfma_f32_16x16x32_bf16 v[88:91], v[140:143], v[216:219], v[88:91]
	v_mfma_f32_16x16x32_bf16 v[76:79], v[132:135], v[224:227], v[76:79]
	v_mfma_f32_16x16x32_bf16 v[72:75], v[140:143], v[224:227], v[72:75]
	v_mfma_f32_16x16x32_bf16 v[116:119], v[164:167], v[196:199], 0
	v_mfma_f32_16x16x32_bf16 v[112:115], v[172:175], v[196:199], 0
	v_mfma_f32_16x16x32_bf16 v[100:103], v[164:167], v[204:207], 0
	v_mfma_f32_16x16x32_bf16 v[96:99], v[172:175], v[204:207], 0
	v_mfma_f32_16x16x32_bf16 v[84:87], v[164:167], v[212:215], 0
	v_mfma_f32_16x16x32_bf16 v[80:83], v[172:175], v[212:215], 0
	v_mfma_f32_16x16x32_bf16 v[68:71], v[164:167], v[220:223], 0
	v_mfma_f32_16x16x32_bf16 v[64:67], v[172:175], v[220:223], 0
	v_mfma_f32_16x16x32_bf16 v[116:119], v[168:171], v[200:203], v[116:119]
	v_mfma_f32_16x16x32_bf16 v[112:115], v[176:179], v[200:203], v[112:115]
	v_mfma_f32_16x16x32_bf16 v[100:103], v[168:171], v[208:211], v[100:103]
	v_mfma_f32_16x16x32_bf16 v[96:99], v[176:179], v[208:211], v[96:99]
	v_mfma_f32_16x16x32_bf16 v[84:87], v[168:171], v[216:219], v[84:87]
	v_mfma_f32_16x16x32_bf16 v[80:83], v[176:179], v[216:219], v[80:83]
	s_setprio 3
	s_barrier
	v_mfma_f32_16x16x32_bf16 v[68:71], v[168:171], v[224:227], v[68:71]
	v_mfma_f32_16x16x32_bf16 v[64:67], v[176:179], v[224:227], v[64:67]
	s_setprio 0
	s_add_i32 s97, s90, s33
	v_lshl_add_u64 v[228:229], s[78:79], 0, v[146:147]
	s_mov_b32 m0, s97
	ds_read_b128 v[196:199], v194 offset:16384
	ds_read_b128 v[200:203], v194 offset:17408
	ds_read_b128 v[204:207], v194 offset:18432
	ds_read_b128 v[208:211], v194 offset:19456
	ds_read_b128 v[212:215], v194 offset:20480
	ds_read_b128 v[216:219], v194 offset:21504
	ds_read_b128 v[220:223], v194 offset:22528
	ds_read_b128 v[224:227], v194 offset:23552
	global_load_lds_dwordx4 v[228:229], off
	s_add_i32 m0, s97, 0x2000
	s_add_u32 vcc_lo, s78, 0x40000
	v_lshl_add_u64 v[230:231], s[78:79], 0, v[150:151]
	s_addc_u32 vcc_hi, s79, 0
	s_add_i32 s97, s91, s33
	global_load_lds_dwordx4 v[230:231], off
	v_lshl_add_u64 v[232:233], vcc, 0, v[146:147]
	s_mov_b32 m0, s97
	global_load_lds_dwordx4 v[232:233], off
	v_lshl_add_u64 v[232:233], vcc, 0, v[150:151]
	s_add_i32 m0, s97, 0x2000
	s_nop 0
	global_load_lds_dwordx4 v[232:233], off
	s_waitcnt vmcnt(6)
	s_waitcnt lgkmcnt(0)
	s_barrier
	s_waitcnt lgkmcnt(0)
	v_mfma_f32_16x16x32_bf16 v[60:63], v[128:131], v[196:199], 0
	v_mfma_f32_16x16x32_bf16 v[56:59], v[136:139], v[196:199], 0
	v_mfma_f32_16x16x32_bf16 v[44:47], v[128:131], v[204:207], 0
	v_mfma_f32_16x16x32_bf16 v[40:43], v[136:139], v[204:207], 0
	v_mfma_f32_16x16x32_bf16 v[28:31], v[128:131], v[212:215], 0
	v_mfma_f32_16x16x32_bf16 v[24:27], v[136:139], v[212:215], 0
	v_mfma_f32_16x16x32_bf16 v[12:15], v[128:131], v[220:223], 0
	v_mfma_f32_16x16x32_bf16 v[8:11], v[136:139], v[220:223], 0
	v_mfma_f32_16x16x32_bf16 v[60:63], v[132:135], v[200:203], v[60:63]
	v_mfma_f32_16x16x32_bf16 v[56:59], v[140:143], v[200:203], v[56:59]
	v_mfma_f32_16x16x32_bf16 v[44:47], v[132:135], v[208:211], v[44:47]
	v_mfma_f32_16x16x32_bf16 v[40:43], v[140:143], v[208:211], v[40:43]
	v_mfma_f32_16x16x32_bf16 v[28:31], v[132:135], v[216:219], v[28:31]
	v_mfma_f32_16x16x32_bf16 v[24:27], v[140:143], v[216:219], v[24:27]
	v_mfma_f32_16x16x32_bf16 v[12:15], v[132:135], v[224:227], v[12:15]
	v_mfma_f32_16x16x32_bf16 v[8:11], v[140:143], v[224:227], v[8:11]
	v_mfma_f32_16x16x32_bf16 v[52:55], v[164:167], v[196:199], 0
	v_mfma_f32_16x16x32_bf16 v[48:51], v[172:175], v[196:199], 0
	v_mfma_f32_16x16x32_bf16 v[36:39], v[164:167], v[204:207], 0
	v_mfma_f32_16x16x32_bf16 v[32:35], v[172:175], v[204:207], 0
	v_mfma_f32_16x16x32_bf16 v[20:23], v[164:167], v[212:215], 0
	v_mfma_f32_16x16x32_bf16 v[16:19], v[172:175], v[212:215], 0
	v_mfma_f32_16x16x32_bf16 v[4:7], v[164:167], v[220:223], 0
	v_mfma_f32_16x16x32_bf16 v[0:3], v[172:175], v[220:223], 0
	v_mfma_f32_16x16x32_bf16 v[52:55], v[168:171], v[200:203], v[52:55]
	v_mfma_f32_16x16x32_bf16 v[48:51], v[176:179], v[200:203], v[48:51]
	v_mfma_f32_16x16x32_bf16 v[36:39], v[168:171], v[208:211], v[36:39]
	v_mfma_f32_16x16x32_bf16 v[32:35], v[176:179], v[208:211], v[32:35]
	v_mfma_f32_16x16x32_bf16 v[20:23], v[168:171], v[216:219], v[20:23]
	v_mfma_f32_16x16x32_bf16 v[16:19], v[176:179], v[216:219], v[16:19]
	s_setprio 3
	s_barrier
	v_mfma_f32_16x16x32_bf16 v[4:7], v[168:171], v[224:227], v[4:7]
	v_mfma_f32_16x16x32_bf16 v[0:3], v[176:179], v[224:227], v[0:3]
	s_setprio 0
	s_add_i32 s97, 0, 0x18000
	s_add_i32 vcc_lo, 0, 0x1c000
	v_add_u32_e32 v140, s97, v180
	v_add_u32_e32 v152, vcc_lo, v180
	ds_read_b128 v[128:131], v140
	ds_read_b128 v[132:135], v140 offset:1024
	ds_read_b128 v[136:139], v140 offset:2048
	ds_read_b128 v[140:143], v140 offset:3072
	ds_read_b128 v[164:167], v152
	ds_read_b128 v[168:171], v152 offset:1024
	ds_read_b128 v[172:175], v152 offset:2048
	ds_read_b128 v[176:179], v152 offset:3072
	v_lshl_add_u64 v[232:233], s[80:81], 0, v[144:145]
	s_mov_b32 m0, s82
	v_lshl_add_u64 v[234:235], s[80:81], 0, v[148:149]
	global_load_lds_dwordx4 v[232:233], off
	s_mov_b32 m0, s83
	s_nop 0
	global_load_lds_dwordx4 v[234:235], off
	s_add_u32 s80, s80, 0x40000
	s_addc_u32 s81, s81, 0
	s_mov_b32 m0, s84
	v_lshl_add_u64 v[236:237], s[80:81], 0, v[144:145]
	ds_read_b128 v[196:199], v194 offset:32768
	ds_read_b128 v[200:203], v194 offset:33792
	ds_read_b128 v[204:207], v194 offset:34816
	ds_read_b128 v[208:211], v194 offset:35840
	ds_read_b128 v[212:215], v194 offset:36864
	ds_read_b128 v[216:219], v194 offset:37888
	ds_read_b128 v[220:223], v194 offset:38912
	ds_read_b128 v[224:227], v194 offset:39936
	global_load_lds_dwordx4 v[236:237], off
	v_lshl_add_u64 v[236:237], s[80:81], 0, v[148:149]
	s_mov_b32 m0, s85
	s_nop 0
	global_load_lds_dwordx4 v[236:237], off
	s_waitcnt vmcnt(8)
	s_waitcnt lgkmcnt(0)
	s_barrier
	s_waitcnt lgkmcnt(0)
	v_mfma_f32_16x16x32_bf16 v[124:127], v[128:131], v[196:199], v[124:127]
	v_mfma_f32_16x16x32_bf16 v[120:123], v[136:139], v[196:199], v[120:123]
	v_mfma_f32_16x16x32_bf16 v[108:111], v[128:131], v[204:207], v[108:111]
	v_mfma_f32_16x16x32_bf16 v[104:107], v[136:139], v[204:207], v[104:107]
	v_mfma_f32_16x16x32_bf16 v[92:95], v[128:131], v[212:215], v[92:95]
	v_mfma_f32_16x16x32_bf16 v[88:91], v[136:139], v[212:215], v[88:91]
	v_mfma_f32_16x16x32_bf16 v[76:79], v[128:131], v[220:223], v[76:79]
	v_mfma_f32_16x16x32_bf16 v[72:75], v[136:139], v[220:223], v[72:75]
	v_mfma_f32_16x16x32_bf16 v[124:127], v[132:135], v[200:203], v[124:127]
	v_mfma_f32_16x16x32_bf16 v[120:123], v[140:143], v[200:203], v[120:123]
	v_mfma_f32_16x16x32_bf16 v[108:111], v[132:135], v[208:211], v[108:111]
	v_mfma_f32_16x16x32_bf16 v[104:107], v[140:143], v[208:211], v[104:107]
	v_mfma_f32_16x16x32_bf16 v[92:95], v[132:135], v[216:219], v[92:95]
	v_mfma_f32_16x16x32_bf16 v[88:91], v[140:143], v[216:219], v[88:91]
	v_mfma_f32_16x16x32_bf16 v[76:79], v[132:135], v[224:227], v[76:79]
	v_mfma_f32_16x16x32_bf16 v[72:75], v[140:143], v[224:227], v[72:75]
	v_mfma_f32_16x16x32_bf16 v[116:119], v[164:167], v[196:199], v[116:119]
	v_mfma_f32_16x16x32_bf16 v[112:115], v[172:175], v[196:199], v[112:115]
	v_mfma_f32_16x16x32_bf16 v[100:103], v[164:167], v[204:207], v[100:103]
	v_mfma_f32_16x16x32_bf16 v[96:99], v[172:175], v[204:207], v[96:99]
	v_mfma_f32_16x16x32_bf16 v[84:87], v[164:167], v[212:215], v[84:87]
	v_mfma_f32_16x16x32_bf16 v[80:83], v[172:175], v[212:215], v[80:83]
	v_mfma_f32_16x16x32_bf16 v[68:71], v[164:167], v[220:223], v[68:71]
	v_mfma_f32_16x16x32_bf16 v[64:67], v[172:175], v[220:223], v[64:67]
	v_mfma_f32_16x16x32_bf16 v[116:119], v[168:171], v[200:203], v[116:119]
	v_mfma_f32_16x16x32_bf16 v[112:115], v[176:179], v[200:203], v[112:115]
	v_mfma_f32_16x16x32_bf16 v[100:103], v[168:171], v[208:211], v[100:103]
	v_mfma_f32_16x16x32_bf16 v[96:99], v[176:179], v[208:211], v[96:99]
	v_mfma_f32_16x16x32_bf16 v[84:87], v[168:171], v[216:219], v[84:87]
	v_mfma_f32_16x16x32_bf16 v[80:83], v[176:179], v[216:219], v[80:83]
	s_setprio 3
	s_barrier
	v_mfma_f32_16x16x32_bf16 v[68:71], v[168:171], v[224:227], v[68:71]
	v_mfma_f32_16x16x32_bf16 v[64:67], v[176:179], v[224:227], v[64:67]
	s_setprio 0
	s_add_i32 s80, s97, s33
	v_lshl_add_u64 v[228:229], v[228:229], 0, s[26:27]
	s_mov_b32 m0, s80
	ds_read_b128 v[196:199], v194 offset:49152
	ds_read_b128 v[200:203], v194 offset:50176
	ds_read_b128 v[204:207], v194 offset:51200
	ds_read_b128 v[208:211], v194 offset:52224
	ds_read_b128 v[212:215], v194 offset:53248
	ds_read_b128 v[216:219], v194 offset:54272
	ds_read_b128 v[220:223], v194 offset:55296
	ds_read_b128 v[224:227], v194 offset:56320
	global_load_lds_dwordx4 v[228:229], off
	s_add_i32 m0, s80, 0x2000
	s_add_u32 s78, s78, 0x40080
	v_lshl_add_u64 v[228:229], v[230:231], 0, s[26:27]
	s_addc_u32 s79, s79, 0
	s_add_i32 s80, vcc_lo, s33
	global_load_lds_dwordx4 v[228:229], off
	v_lshl_add_u64 v[228:229], s[78:79], 0, v[146:147]
	s_mov_b32 m0, s80
	s_nop 0
	global_load_lds_dwordx4 v[228:229], off
	v_lshl_add_u64 v[228:229], s[78:79], 0, v[150:151]
	s_add_i32 m0, s80, 0x2000
	s_nop 0
	global_load_lds_dwordx4 v[228:229], off
	s_waitcnt vmcnt(6)
	s_waitcnt lgkmcnt(0)
	s_barrier
	s_waitcnt lgkmcnt(0)
	v_mfma_f32_16x16x32_bf16 v[60:63], v[128:131], v[196:199], v[60:63]
	v_mfma_f32_16x16x32_bf16 v[56:59], v[136:139], v[196:199], v[56:59]
	v_mfma_f32_16x16x32_bf16 v[44:47], v[128:131], v[204:207], v[44:47]
	v_mfma_f32_16x16x32_bf16 v[40:43], v[136:139], v[204:207], v[40:43]
	v_mfma_f32_16x16x32_bf16 v[28:31], v[128:131], v[212:215], v[28:31]
	v_mfma_f32_16x16x32_bf16 v[24:27], v[136:139], v[212:215], v[24:27]
	v_mfma_f32_16x16x32_bf16 v[12:15], v[128:131], v[220:223], v[12:15]
	v_mfma_f32_16x16x32_bf16 v[8:11], v[136:139], v[220:223], v[8:11]
	v_mfma_f32_16x16x32_bf16 v[60:63], v[132:135], v[200:203], v[60:63]
	v_mfma_f32_16x16x32_bf16 v[56:59], v[140:143], v[200:203], v[56:59]
	v_mfma_f32_16x16x32_bf16 v[44:47], v[132:135], v[208:211], v[44:47]
	v_mfma_f32_16x16x32_bf16 v[40:43], v[140:143], v[208:211], v[40:43]
	v_mfma_f32_16x16x32_bf16 v[28:31], v[132:135], v[216:219], v[28:31]
	v_mfma_f32_16x16x32_bf16 v[24:27], v[140:143], v[216:219], v[24:27]
	v_mfma_f32_16x16x32_bf16 v[12:15], v[132:135], v[224:227], v[12:15]
	v_mfma_f32_16x16x32_bf16 v[8:11], v[140:143], v[224:227], v[8:11]
	v_mfma_f32_16x16x32_bf16 v[52:55], v[164:167], v[196:199], v[52:55]
	v_mfma_f32_16x16x32_bf16 v[48:51], v[172:175], v[196:199], v[48:51]
	v_mfma_f32_16x16x32_bf16 v[36:39], v[164:167], v[204:207], v[36:39]
	v_mfma_f32_16x16x32_bf16 v[32:35], v[172:175], v[204:207], v[32:35]
	v_mfma_f32_16x16x32_bf16 v[20:23], v[164:167], v[212:215], v[20:23]
	v_mfma_f32_16x16x32_bf16 v[16:19], v[172:175], v[212:215], v[16:19]
	v_mfma_f32_16x16x32_bf16 v[4:7], v[164:167], v[220:223], v[4:7]
	v_mfma_f32_16x16x32_bf16 v[0:3], v[172:175], v[220:223], v[0:3]
	v_mfma_f32_16x16x32_bf16 v[52:55], v[168:171], v[200:203], v[52:55]
	v_mfma_f32_16x16x32_bf16 v[48:51], v[176:179], v[200:203], v[48:51]
	v_mfma_f32_16x16x32_bf16 v[36:39], v[168:171], v[208:211], v[36:39]
	v_mfma_f32_16x16x32_bf16 v[32:35], v[176:179], v[208:211], v[32:35]
	v_mfma_f32_16x16x32_bf16 v[20:23], v[168:171], v[216:219], v[20:23]
	v_mfma_f32_16x16x32_bf16 v[16:19], v[176:179], v[216:219], v[16:19]
	s_setprio 3
	s_barrier
	v_mfma_f32_16x16x32_bf16 v[4:7], v[168:171], v[224:227], v[4:7]
	v_mfma_f32_16x16x32_bf16 v[0:3], v[176:179], v[224:227], v[0:3]
	s_setprio 0
	v_lshl_add_u64 v[228:229], v[232:233], 0, s[26:27]
	s_mov_b32 m0, s87
	s_nop 0
	global_load_lds_dwordx4 v[228:229], off
	v_lshl_add_u64 v[228:229], v[234:235], 0, s[26:27]
	s_mov_b32 m0, s88
	s_nop 0
	global_load_lds_dwordx4 v[228:229], off
	s_add_i32 s96, s96, 2
	s_add_u32 s70, s70, 0x100
	s_addc_u32 s71, s71, 0
	s_add_u32 s94, s94, 0x100
	s_addc_u32 s95, s95, 0
	s_cmp_gt_u32 s96, 13

.LBB0_616:
	s_ashr_i32 s17, s16, 31
	s_lshl_b64 s[18:19], s[16:17], 19
	s_add_u32 s18, s48, s18
	s_addc_u32 s19, s49, s19
	s_and_b64 s[20:21], s[4:5], exec
	s_cselect_b32 s17, s19, s25
	s_cselect_b32 s23, s18, s24
	s_ashr_i32 s15, s14, 31
	s_lshl_b64 s[20:21], s[14:15], 19
	s_add_u32 s20, s30, s20
	s_addc_u32 s21, s31, s21
	s_and_b64 s[28:29], s[4:5], exec
	s_cselect_b32 s15, s21, s27
	s_cselect_b32 s46, s20, s26
	s_add_u32 s24, s24, 0x40080
	s_addc_u32 s25, s25, 0
	s_add_u32 s47, s26, 0x100
	s_addc_u32 s50, s27, 0
	s_mov_b32 s51, -2
	s_waitcnt lgkmcnt(0)
	ds_read_b128 v[144:147], v151
	ds_read_b128 v[156:159], v151 offset:1024
	ds_read_b128 v[160:163], v151 offset:2048
	ds_read_b128 v[164:167], v151 offset:3072
	ds_read_b128 v[168:171], v152
	ds_read_b128 v[172:175], v152 offset:1024
	ds_read_b128 v[176:179], v152 offset:2048
	ds_read_b128 v[184:187], v152 offset:3072
	s_add_u32 s26, s24, 0xfffc0080
	s_addc_u32 s27, s25, -1
	s_cmp_eq_u32 s51, 12
	s_cselect_b32 s29, s17, s27
	s_cselect_b32 s28, s23, s26
	s_cselect_b32 s27, s15, s50
	s_cselect_b32 s26, s46, s47
	v_lshl_add_u64 v[220:221], s[24:25], 0, v[136:137]
	s_add_i32 m0, s34, 0xc000
	ds_read_b128 v[188:191], v153
	ds_read_b128 v[192:195], v153 offset:1024
	ds_read_b128 v[196:199], v153 offset:2048
	ds_read_b128 v[200:203], v153 offset:3072
	ds_read_b128 v[204:207], v153 offset:4096
	ds_read_b128 v[208:211], v153 offset:5120
	ds_read_b128 v[212:215], v153 offset:6144
	ds_read_b128 v[216:219], v153 offset:7168
	global_load_lds_dwordx4 v[220:221], off
	v_lshl_add_u64 v[220:221], s[24:25], 0, v[138:139]
	s_add_i32 m0, s34, 0xe000
	s_nop 0
	global_load_lds_dwordx4 v[220:221], off
	s_waitcnt vmcnt(8)
	s_waitcnt lgkmcnt(0)
	s_barrier
	s_waitcnt lgkmcnt(0)
	v_mfma_f32_16x16x32_bf16 v[124:127], v[144:147], v[188:191], 0
	v_mfma_f32_16x16x32_bf16 v[120:123], v[160:163], v[188:191], 0
	v_mfma_f32_16x16x32_bf16 v[108:111], v[144:147], v[196:199], 0
	v_mfma_f32_16x16x32_bf16 v[104:107], v[160:163], v[196:199], 0
	v_mfma_f32_16x16x32_bf16 v[92:95], v[144:147], v[204:207], 0
	v_mfma_f32_16x16x32_bf16 v[88:91], v[160:163], v[204:207], 0
	v_mfma_f32_16x16x32_bf16 v[76:79], v[144:147], v[212:215], 0
	v_mfma_f32_16x16x32_bf16 v[72:75], v[160:163], v[212:215], 0
	v_mfma_f32_16x16x32_bf16 v[124:127], v[156:159], v[192:195], v[124:127]
	v_mfma_f32_16x16x32_bf16 v[120:123], v[164:167], v[192:195], v[120:123]
	v_mfma_f32_16x16x32_bf16 v[108:111], v[156:159], v[200:203], v[108:111]
	v_mfma_f32_16x16x32_bf16 v[104:107], v[164:167], v[200:203], v[104:107]
	v_mfma_f32_16x16x32_bf16 v[92:95], v[156:159], v[208:211], v[92:95]
	v_mfma_f32_16x16x32_bf16 v[88:91], v[164:167], v[208:211], v[88:91]
	v_mfma_f32_16x16x32_bf16 v[76:79], v[156:159], v[216:219], v[76:79]
	v_mfma_f32_16x16x32_bf16 v[72:75], v[164:167], v[216:219], v[72:75]
	v_mfma_f32_16x16x32_bf16 v[116:119], v[168:171], v[188:191], 0
	v_mfma_f32_16x16x32_bf16 v[112:115], v[176:179], v[188:191], 0
	v_mfma_f32_16x16x32_bf16 v[100:103], v[168:171], v[196:199], 0
	v_mfma_f32_16x16x32_bf16 v[96:99], v[176:179], v[196:199], 0
	v_mfma_f32_16x16x32_bf16 v[84:87], v[168:171], v[204:207], 0
	v_mfma_f32_16x16x32_bf16 v[80:83], v[176:179], v[204:207], 0
	v_mfma_f32_16x16x32_bf16 v[68:71], v[168:171], v[212:215], 0
	v_mfma_f32_16x16x32_bf16 v[64:67], v[176:179], v[212:215], 0
	v_mfma_f32_16x16x32_bf16 v[116:119], v[172:175], v[192:195], v[116:119]
	v_mfma_f32_16x16x32_bf16 v[112:115], v[184:187], v[192:195], v[112:115]
	v_mfma_f32_16x16x32_bf16 v[100:103], v[172:175], v[200:203], v[100:103]
	v_mfma_f32_16x16x32_bf16 v[96:99], v[184:187], v[200:203], v[96:99]
	v_mfma_f32_16x16x32_bf16 v[84:87], v[172:175], v[208:211], v[84:87]
	v_mfma_f32_16x16x32_bf16 v[80:83], v[184:187], v[208:211], v[80:83]
	s_setprio 3
	s_barrier
	v_mfma_f32_16x16x32_bf16 v[68:71], v[172:175], v[216:219], v[68:71]
	v_mfma_f32_16x16x32_bf16 v[64:67], v[184:187], v[216:219], v[64:67]
	s_setprio 0
	s_add_i32 s52, s41, s33
	v_lshl_add_u64 v[220:221], s[26:27], 0, v[130:131]
	s_mov_b32 m0, s52
	ds_read_b128 v[188:191], v153 offset:16384
	ds_read_b128 v[192:195], v153 offset:17408
	ds_read_b128 v[196:199], v153 offset:18432
	ds_read_b128 v[200:203], v153 offset:19456
	ds_read_b128 v[204:207], v153 offset:20480
	ds_read_b128 v[208:211], v153 offset:21504
	ds_read_b128 v[212:215], v153 offset:22528
	ds_read_b128 v[216:219], v153 offset:23552
	global_load_lds_dwordx4 v[220:221], off
	s_add_i32 m0, s52, 0x2000
	s_add_u32 s52, s26, 0x40000
	v_lshl_add_u64 v[222:223], s[26:27], 0, v[134:135]
	s_addc_u32 s53, s27, 0
	s_add_i32 s54, s42, s33
	global_load_lds_dwordx4 v[222:223], off
	v_lshl_add_u64 v[224:225], s[52:53], 0, v[130:131]
	s_mov_b32 m0, s54
	global_load_lds_dwordx4 v[224:225], off
	v_lshl_add_u64 v[224:225], s[52:53], 0, v[134:135]
	s_add_i32 m0, s54, 0x2000
	s_nop 0
	global_load_lds_dwordx4 v[224:225], off
	s_waitcnt vmcnt(6)
	s_waitcnt lgkmcnt(0)
	s_barrier
	s_waitcnt lgkmcnt(0)
	v_mfma_f32_16x16x32_bf16 v[60:63], v[144:147], v[188:191], 0
	v_mfma_f32_16x16x32_bf16 v[56:59], v[160:163], v[188:191], 0
	v_mfma_f32_16x16x32_bf16 v[44:47], v[144:147], v[196:199], 0
	v_mfma_f32_16x16x32_bf16 v[40:43], v[160:163], v[196:199], 0
	v_mfma_f32_16x16x32_bf16 v[28:31], v[144:147], v[204:207], 0
	v_mfma_f32_16x16x32_bf16 v[24:27], v[160:163], v[204:207], 0
	v_mfma_f32_16x16x32_bf16 v[12:15], v[144:147], v[212:215], 0
	v_mfma_f32_16x16x32_bf16 v[8:11], v[160:163], v[212:215], 0
	v_mfma_f32_16x16x32_bf16 v[60:63], v[156:159], v[192:195], v[60:63]
	v_mfma_f32_16x16x32_bf16 v[56:59], v[164:167], v[192:195], v[56:59]
	v_mfma_f32_16x16x32_bf16 v[44:47], v[156:159], v[200:203], v[44:47]
	v_mfma_f32_16x16x32_bf16 v[40:43], v[164:167], v[200:203], v[40:43]
	v_mfma_f32_16x16x32_bf16 v[28:31], v[156:159], v[208:211], v[28:31]
	v_mfma_f32_16x16x32_bf16 v[24:27], v[164:167], v[208:211], v[24:27]
	v_mfma_f32_16x16x32_bf16 v[12:15], v[156:159], v[216:219], v[12:15]
	v_mfma_f32_16x16x32_bf16 v[8:11], v[164:167], v[216:219], v[8:11]
	v_mfma_f32_16x16x32_bf16 v[52:55], v[168:171], v[188:191], 0
	v_mfma_f32_16x16x32_bf16 v[48:51], v[176:179], v[188:191], 0
	v_mfma_f32_16x16x32_bf16 v[36:39], v[168:171], v[196:199], 0
	v_mfma_f32_16x16x32_bf16 v[32:35], v[176:179], v[196:199], 0
	v_mfma_f32_16x16x32_bf16 v[20:23], v[168:171], v[204:207], 0
	v_mfma_f32_16x16x32_bf16 v[16:19], v[176:179], v[204:207], 0
	v_mfma_f32_16x16x32_bf16 v[4:7], v[168:171], v[212:215], 0
	v_mfma_f32_16x16x32_bf16 v[0:3], v[176:179], v[212:215], 0
	v_mfma_f32_16x16x32_bf16 v[52:55], v[172:175], v[192:195], v[52:55]
	v_mfma_f32_16x16x32_bf16 v[48:51], v[184:187], v[192:195], v[48:51]
	v_mfma_f32_16x16x32_bf16 v[36:39], v[172:175], v[200:203], v[36:39]
	v_mfma_f32_16x16x32_bf16 v[32:35], v[184:187], v[200:203], v[32:35]
	v_mfma_f32_16x16x32_bf16 v[20:23], v[172:175], v[208:211], v[20:23]
	v_mfma_f32_16x16x32_bf16 v[16:19], v[184:187], v[208:211], v[16:19]
	s_setprio 3
	s_barrier
	v_mfma_f32_16x16x32_bf16 v[4:7], v[172:175], v[216:219], v[4:7]
	v_mfma_f32_16x16x32_bf16 v[0:3], v[184:187], v[216:219], v[0:3]
	s_setprio 0
	s_add_i32 s52, 0, 0x18000
	v_add_u32_e32 v155, s52, v149
	s_add_i32 s53, 0, 0x1c000
	ds_read_b128 v[144:147], v155
	ds_read_b128 v[156:159], v155 offset:1024
	ds_read_b128 v[160:163], v155 offset:2048
	ds_read_b128 v[164:167], v155 offset:3072
	v_add_u32_e32 v155, s53, v149
	ds_read_b128 v[168:171], v155
	ds_read_b128 v[172:175], v155 offset:1024
	ds_read_b128 v[176:179], v155 offset:2048
	ds_read_b128 v[184:187], v155 offset:3072
	v_lshl_add_u64 v[224:225], s[28:29], 0, v[128:129]
	s_mov_b32 m0, s34
	v_lshl_add_u64 v[226:227], s[28:29], 0, v[132:133]
	global_load_lds_dwordx4 v[224:225], off
	s_mov_b32 m0, s35
	s_nop 0
	global_load_lds_dwordx4 v[226:227], off
	s_add_u32 s28, s28, 0x40000
	s_addc_u32 s29, s29, 0
	s_mov_b32 m0, s36
	v_lshl_add_u64 v[228:229], s[28:29], 0, v[128:129]
	ds_read_b128 v[188:191], v153 offset:32768
	ds_read_b128 v[192:195], v153 offset:33792
	ds_read_b128 v[196:199], v153 offset:34816
	ds_read_b128 v[200:203], v153 offset:35840
	ds_read_b128 v[204:207], v153 offset:36864
	ds_read_b128 v[208:211], v153 offset:37888
	ds_read_b128 v[212:215], v153 offset:38912
	ds_read_b128 v[216:219], v153 offset:39936
	global_load_lds_dwordx4 v[228:229], off
	v_lshl_add_u64 v[228:229], s[28:29], 0, v[132:133]
	s_mov_b32 m0, s37
	s_nop 0
	global_load_lds_dwordx4 v[228:229], off
	s_waitcnt vmcnt(8)
	s_waitcnt lgkmcnt(0)
	s_barrier
	s_waitcnt lgkmcnt(0)
	v_mfma_f32_16x16x32_bf16 v[124:127], v[144:147], v[188:191], v[124:127]
	v_mfma_f32_16x16x32_bf16 v[120:123], v[160:163], v[188:191], v[120:123]
	v_mfma_f32_16x16x32_bf16 v[108:111], v[144:147], v[196:199], v[108:111]
	v_mfma_f32_16x16x32_bf16 v[104:107], v[160:163], v[196:199], v[104:107]
	v_mfma_f32_16x16x32_bf16 v[92:95], v[144:147], v[204:207], v[92:95]
	v_mfma_f32_16x16x32_bf16 v[88:91], v[160:163], v[204:207], v[88:91]
	v_mfma_f32_16x16x32_bf16 v[76:79], v[144:147], v[212:215], v[76:79]
	v_mfma_f32_16x16x32_bf16 v[72:75], v[160:163], v[212:215], v[72:75]
	v_mfma_f32_16x16x32_bf16 v[124:127], v[156:159], v[192:195], v[124:127]
	v_mfma_f32_16x16x32_bf16 v[120:123], v[164:167], v[192:195], v[120:123]
	v_mfma_f32_16x16x32_bf16 v[108:111], v[156:159], v[200:203], v[108:111]
	v_mfma_f32_16x16x32_bf16 v[104:107], v[164:167], v[200:203], v[104:107]
	v_mfma_f32_16x16x32_bf16 v[92:95], v[156:159], v[208:211], v[92:95]
	v_mfma_f32_16x16x32_bf16 v[88:91], v[164:167], v[208:211], v[88:91]
	v_mfma_f32_16x16x32_bf16 v[76:79], v[156:159], v[216:219], v[76:79]
	v_mfma_f32_16x16x32_bf16 v[72:75], v[164:167], v[216:219], v[72:75]
	v_mfma_f32_16x16x32_bf16 v[116:119], v[168:171], v[188:191], v[116:119]
	v_mfma_f32_16x16x32_bf16 v[112:115], v[176:179], v[188:191], v[112:115]
	v_mfma_f32_16x16x32_bf16 v[100:103], v[168:171], v[196:199], v[100:103]
	v_mfma_f32_16x16x32_bf16 v[96:99], v[176:179], v[196:199], v[96:99]
	v_mfma_f32_16x16x32_bf16 v[84:87], v[168:171], v[204:207], v[84:87]
	v_mfma_f32_16x16x32_bf16 v[80:83], v[176:179], v[204:207], v[80:83]
	v_mfma_f32_16x16x32_bf16 v[68:71], v[168:171], v[212:215], v[68:71]
	v_mfma_f32_16x16x32_bf16 v[64:67], v[176:179], v[212:215], v[64:67]
	v_mfma_f32_16x16x32_bf16 v[116:119], v[172:175], v[192:195], v[116:119]
	v_mfma_f32_16x16x32_bf16 v[112:115], v[184:187], v[192:195], v[112:115]
	v_mfma_f32_16x16x32_bf16 v[100:103], v[172:175], v[200:203], v[100:103]
	v_mfma_f32_16x16x32_bf16 v[96:99], v[184:187], v[200:203], v[96:99]
	v_mfma_f32_16x16x32_bf16 v[84:87], v[172:175], v[208:211], v[84:87]
	v_mfma_f32_16x16x32_bf16 v[80:83], v[184:187], v[208:211], v[80:83]
	s_setprio 3
	s_barrier
	v_mfma_f32_16x16x32_bf16 v[68:71], v[172:175], v[216:219], v[68:71]
	v_mfma_f32_16x16x32_bf16 v[64:67], v[184:187], v[216:219], v[64:67]
	s_setprio 0
	s_add_i32 s28, s52, s33
	v_lshl_add_u64 v[220:221], v[220:221], 0, s[10:11]
	s_mov_b32 m0, s28
	ds_read_b128 v[188:191], v153 offset:49152
	ds_read_b128 v[192:195], v153 offset:50176
	ds_read_b128 v[196:199], v153 offset:51200
	ds_read_b128 v[200:203], v153 offset:52224
	ds_read_b128 v[204:207], v153 offset:53248
	ds_read_b128 v[208:211], v153 offset:54272
	ds_read_b128 v[212:215], v153 offset:55296
	ds_read_b128 v[216:219], v153 offset:56320
	global_load_lds_dwordx4 v[220:221], off
	s_add_i32 m0, s28, 0x2000
	s_add_u32 s26, s26, 0x40080
	v_lshl_add_u64 v[220:221], v[222:223], 0, s[10:11]
	s_addc_u32 s27, s27, 0
	s_add_i32 s28, s53, s33
	global_load_lds_dwordx4 v[220:221], off
	v_lshl_add_u64 v[220:221], s[26:27], 0, v[130:131]
	s_mov_b32 m0, s28
	s_nop 0
	global_load_lds_dwordx4 v[220:221], off
	v_lshl_add_u64 v[220:221], s[26:27], 0, v[134:135]
	s_add_i32 m0, s28, 0x2000
	s_nop 0
	global_load_lds_dwordx4 v[220:221], off
	s_waitcnt vmcnt(6)
	s_waitcnt lgkmcnt(0)
	s_barrier
	s_waitcnt lgkmcnt(0)
	v_mfma_f32_16x16x32_bf16 v[60:63], v[144:147], v[188:191], v[60:63]
	v_mfma_f32_16x16x32_bf16 v[56:59], v[160:163], v[188:191], v[56:59]
	v_mfma_f32_16x16x32_bf16 v[44:47], v[144:147], v[196:199], v[44:47]
	v_mfma_f32_16x16x32_bf16 v[40:43], v[160:163], v[196:199], v[40:43]
	v_mfma_f32_16x16x32_bf16 v[28:31], v[144:147], v[204:207], v[28:31]
	v_mfma_f32_16x16x32_bf16 v[24:27], v[160:163], v[204:207], v[24:27]
	v_mfma_f32_16x16x32_bf16 v[12:15], v[144:147], v[212:215], v[12:15]
	v_mfma_f32_16x16x32_bf16 v[8:11], v[160:163], v[212:215], v[8:11]
	v_mfma_f32_16x16x32_bf16 v[60:63], v[156:159], v[192:195], v[60:63]
	v_mfma_f32_16x16x32_bf16 v[56:59], v[164:167], v[192:195], v[56:59]
	v_mfma_f32_16x16x32_bf16 v[44:47], v[156:159], v[200:203], v[44:47]
	v_mfma_f32_16x16x32_bf16 v[40:43], v[164:167], v[200:203], v[40:43]
	v_mfma_f32_16x16x32_bf16 v[28:31], v[156:159], v[208:211], v[28:31]
	v_mfma_f32_16x16x32_bf16 v[24:27], v[164:167], v[208:211], v[24:27]
	v_mfma_f32_16x16x32_bf16 v[12:15], v[156:159], v[216:219], v[12:15]
	v_mfma_f32_16x16x32_bf16 v[8:11], v[164:167], v[216:219], v[8:11]
	v_mfma_f32_16x16x32_bf16 v[52:55], v[168:171], v[188:191], v[52:55]
	v_mfma_f32_16x16x32_bf16 v[48:51], v[176:179], v[188:191], v[48:51]
	v_mfma_f32_16x16x32_bf16 v[36:39], v[168:171], v[196:199], v[36:39]
	v_mfma_f32_16x16x32_bf16 v[32:35], v[176:179], v[196:199], v[32:35]
	v_mfma_f32_16x16x32_bf16 v[20:23], v[168:171], v[204:207], v[20:23]
	v_mfma_f32_16x16x32_bf16 v[16:19], v[176:179], v[204:207], v[16:19]
	v_mfma_f32_16x16x32_bf16 v[4:7], v[168:171], v[212:215], v[4:7]
	v_mfma_f32_16x16x32_bf16 v[0:3], v[176:179], v[212:215], v[0:3]
	v_mfma_f32_16x16x32_bf16 v[52:55], v[172:175], v[192:195], v[52:55]
	v_mfma_f32_16x16x32_bf16 v[48:51], v[184:187], v[192:195], v[48:51]
	v_mfma_f32_16x16x32_bf16 v[36:39], v[172:175], v[200:203], v[36:39]
	v_mfma_f32_16x16x32_bf16 v[32:35], v[184:187], v[200:203], v[32:35]
	v_mfma_f32_16x16x32_bf16 v[20:23], v[172:175], v[208:211], v[20:23]
	v_mfma_f32_16x16x32_bf16 v[16:19], v[184:187], v[208:211], v[16:19]
	s_setprio 3
	s_barrier
	v_mfma_f32_16x16x32_bf16 v[4:7], v[172:175], v[216:219], v[4:7]
	v_mfma_f32_16x16x32_bf16 v[0:3], v[184:187], v[216:219], v[0:3]
	s_setprio 0
	v_lshl_add_u64 v[220:221], v[224:225], 0, s[10:11]
	s_mov_b32 m0, s39
	s_nop 0
	global_load_lds_dwordx4 v[220:221], off
	v_lshl_add_u64 v[220:221], v[226:227], 0, s[10:11]
	s_mov_b32 m0, s40
	s_nop 0
	global_load_lds_dwordx4 v[220:221], off
	s_add_i32 s51, s51, 2
	s_add_u32 s24, s24, 0x100
	s_addc_u32 s25, s25, 0
	s_add_u32 s47, s47, 0x100
	s_addc_u32 s50, s50, 0
	s_cmp_gt_u32 s51, 13

.LBB0_704:
	s_ashr_i32 s13, s12, 31
	s_lshl_b64 s[14:15], s[12:13], 19
	s_add_u32 s14, s74, s14
	s_addc_u32 s15, s75, s15
	s_and_b64 s[16:17], s[0:1], exec
	s_cselect_b32 s13, s15, s21
	s_cselect_b32 s42, s14, s20
	s_ashr_i32 s11, s10, 31
	s_lshl_b64 s[16:17], s[10:11], 19
	s_add_u32 s16, s26, s16
	s_addc_u32 s17, s27, s17
	s_and_b64 s[24:25], s[0:1], exec
	s_cselect_b32 s11, s17, s23
	s_cselect_b32 s43, s16, s22
	s_add_u32 s20, s20, 0x40080
	s_addc_u32 s21, s21, 0
	s_add_u32 s46, s22, 0x100
	s_addc_u32 s47, s23, 0
	s_mov_b32 s50, -2
	ds_read_b128 v[154:157], v151
	ds_read_b128 v[158:161], v151 offset:1024
	ds_read_b128 v[162:165], v151 offset:2048
	ds_read_b128 v[166:169], v151 offset:3072
	ds_read_b128 v[170:173], v152
	ds_read_b128 v[174:177], v152 offset:1024
	ds_read_b128 v[184:187], v152 offset:2048
	ds_read_b128 v[188:191], v152 offset:3072
	s_add_u32 s22, s20, 0xfffc0080
	s_addc_u32 s23, s21, -1
	s_cmp_eq_u32 s50, 12
	s_cselect_b32 s25, s13, s23
	s_cselect_b32 s24, s42, s22
	s_cselect_b32 s23, s11, s47
	s_cselect_b32 s22, s43, s46
	v_lshl_add_u64 v[178:179], s[20:21], 0, v[136:137]
	s_add_i32 m0, s19, 0xc000
	ds_read_b128 v[192:195], v153
	ds_read_b128 v[196:199], v153 offset:1024
	ds_read_b128 v[200:203], v153 offset:2048
	ds_read_b128 v[204:207], v153 offset:3072
	ds_read_b128 v[208:211], v153 offset:4096
	ds_read_b128 v[212:215], v153 offset:5120
	ds_read_b128 v[216:219], v153 offset:6144
	ds_read_b128 v[220:223], v153 offset:7168
	global_load_lds_dwordx4 v[178:179], off
	v_lshl_add_u64 v[178:179], s[20:21], 0, v[138:139]
	s_add_i32 m0, s19, 0xe000
	s_nop 0
	global_load_lds_dwordx4 v[178:179], off
	s_waitcnt vmcnt(8)
	s_waitcnt lgkmcnt(0)
	s_barrier
	s_waitcnt lgkmcnt(0)
	v_mfma_f32_16x16x32_bf16 v[124:127], v[154:157], v[192:195], 0
	v_mfma_f32_16x16x32_bf16 v[116:119], v[162:165], v[192:195], 0
	v_mfma_f32_16x16x32_bf16 v[108:111], v[154:157], v[200:203], 0
	v_mfma_f32_16x16x32_bf16 v[100:103], v[162:165], v[200:203], 0
	v_mfma_f32_16x16x32_bf16 v[92:95], v[154:157], v[208:211], 0
	v_mfma_f32_16x16x32_bf16 v[84:87], v[162:165], v[208:211], 0
	v_mfma_f32_16x16x32_bf16 v[76:79], v[154:157], v[216:219], 0
	v_mfma_f32_16x16x32_bf16 v[68:71], v[162:165], v[216:219], 0
	v_mfma_f32_16x16x32_bf16 v[124:127], v[158:161], v[196:199], v[124:127]
	v_mfma_f32_16x16x32_bf16 v[116:119], v[166:169], v[196:199], v[116:119]
	v_mfma_f32_16x16x32_bf16 v[108:111], v[158:161], v[204:207], v[108:111]
	v_mfma_f32_16x16x32_bf16 v[100:103], v[166:169], v[204:207], v[100:103]
	v_mfma_f32_16x16x32_bf16 v[92:95], v[158:161], v[212:215], v[92:95]
	v_mfma_f32_16x16x32_bf16 v[84:87], v[166:169], v[212:215], v[84:87]
	v_mfma_f32_16x16x32_bf16 v[76:79], v[158:161], v[220:223], v[76:79]
	v_mfma_f32_16x16x32_bf16 v[68:71], v[166:169], v[220:223], v[68:71]
	v_mfma_f32_16x16x32_bf16 v[120:123], v[170:173], v[192:195], 0
	v_mfma_f32_16x16x32_bf16 v[112:115], v[184:187], v[192:195], 0
	v_mfma_f32_16x16x32_bf16 v[104:107], v[170:173], v[200:203], 0
	v_mfma_f32_16x16x32_bf16 v[96:99], v[184:187], v[200:203], 0
	v_mfma_f32_16x16x32_bf16 v[88:91], v[170:173], v[208:211], 0
	v_mfma_f32_16x16x32_bf16 v[80:83], v[184:187], v[208:211], 0
	v_mfma_f32_16x16x32_bf16 v[72:75], v[170:173], v[216:219], 0
	v_mfma_f32_16x16x32_bf16 v[64:67], v[184:187], v[216:219], 0
	v_mfma_f32_16x16x32_bf16 v[120:123], v[174:177], v[196:199], v[120:123]
	v_mfma_f32_16x16x32_bf16 v[112:115], v[188:191], v[196:199], v[112:115]
	v_mfma_f32_16x16x32_bf16 v[104:107], v[174:177], v[204:207], v[104:107]
	v_mfma_f32_16x16x32_bf16 v[96:99], v[188:191], v[204:207], v[96:99]
	v_mfma_f32_16x16x32_bf16 v[88:91], v[174:177], v[212:215], v[88:91]
	v_mfma_f32_16x16x32_bf16 v[80:83], v[188:191], v[212:215], v[80:83]
	s_setprio 3
	s_barrier
	v_mfma_f32_16x16x32_bf16 v[72:75], v[174:177], v[220:223], v[72:75]
	v_mfma_f32_16x16x32_bf16 v[64:67], v[188:191], v[220:223], v[64:67]
	s_setprio 0
	s_add_i32 s51, s36, s28
	v_lshl_add_u64 v[178:179], s[22:23], 0, v[132:133]
	s_mov_b32 m0, s51
	ds_read_b128 v[192:195], v153 offset:16384
	ds_read_b128 v[196:199], v153 offset:17408
	ds_read_b128 v[200:203], v153 offset:18432
	ds_read_b128 v[204:207], v153 offset:19456
	ds_read_b128 v[208:211], v153 offset:20480
	ds_read_b128 v[212:215], v153 offset:21504
	ds_read_b128 v[216:219], v153 offset:22528
	ds_read_b128 v[220:223], v153 offset:23552
	global_load_lds_dwordx4 v[178:179], off
	s_add_i32 m0, s51, 0x2000
	s_add_u32 s52, s22, 0x40000
	v_lshl_add_u64 v[224:225], s[22:23], 0, v[128:129]
	s_addc_u32 s53, s23, 0
	s_add_i32 s51, s37, s28
	global_load_lds_dwordx4 v[224:225], off
	v_lshl_add_u64 v[226:227], s[52:53], 0, v[132:133]
	s_mov_b32 m0, s51
	global_load_lds_dwordx4 v[226:227], off
	v_lshl_add_u64 v[226:227], s[52:53], 0, v[128:129]
	s_add_i32 m0, s51, 0x2000
	s_nop 0
	global_load_lds_dwordx4 v[226:227], off
	s_waitcnt vmcnt(6)
	s_waitcnt lgkmcnt(0)
	s_barrier
	s_waitcnt lgkmcnt(0)
	v_mfma_f32_16x16x32_bf16 v[60:63], v[154:157], v[192:195], 0
	v_mfma_f32_16x16x32_bf16 v[52:55], v[162:165], v[192:195], 0
	v_mfma_f32_16x16x32_bf16 v[44:47], v[154:157], v[200:203], 0
	v_mfma_f32_16x16x32_bf16 v[36:39], v[162:165], v[200:203], 0
	v_mfma_f32_16x16x32_bf16 v[28:31], v[154:157], v[208:211], 0
	v_mfma_f32_16x16x32_bf16 v[20:23], v[162:165], v[208:211], 0
	v_mfma_f32_16x16x32_bf16 v[12:15], v[154:157], v[216:219], 0
	v_mfma_f32_16x16x32_bf16 v[4:7], v[162:165], v[216:219], 0
	v_mfma_f32_16x16x32_bf16 v[60:63], v[158:161], v[196:199], v[60:63]
	v_mfma_f32_16x16x32_bf16 v[52:55], v[166:169], v[196:199], v[52:55]
	v_mfma_f32_16x16x32_bf16 v[44:47], v[158:161], v[204:207], v[44:47]
	v_mfma_f32_16x16x32_bf16 v[36:39], v[166:169], v[204:207], v[36:39]
	v_mfma_f32_16x16x32_bf16 v[28:31], v[158:161], v[212:215], v[28:31]
	v_mfma_f32_16x16x32_bf16 v[20:23], v[166:169], v[212:215], v[20:23]
	v_mfma_f32_16x16x32_bf16 v[12:15], v[158:161], v[220:223], v[12:15]
	v_mfma_f32_16x16x32_bf16 v[4:7], v[166:169], v[220:223], v[4:7]
	v_mfma_f32_16x16x32_bf16 v[56:59], v[170:173], v[192:195], 0
	v_mfma_f32_16x16x32_bf16 v[48:51], v[184:187], v[192:195], 0
	v_mfma_f32_16x16x32_bf16 v[40:43], v[170:173], v[200:203], 0
	v_mfma_f32_16x16x32_bf16 v[32:35], v[184:187], v[200:203], 0
	v_mfma_f32_16x16x32_bf16 v[24:27], v[170:173], v[208:211], 0
	v_mfma_f32_16x16x32_bf16 v[16:19], v[184:187], v[208:211], 0
	v_mfma_f32_16x16x32_bf16 v[8:11], v[170:173], v[216:219], 0
	v_mfma_f32_16x16x32_bf16 v[0:3], v[184:187], v[216:219], 0
	v_mfma_f32_16x16x32_bf16 v[56:59], v[174:177], v[196:199], v[56:59]
	v_mfma_f32_16x16x32_bf16 v[48:51], v[188:191], v[196:199], v[48:51]
	v_mfma_f32_16x16x32_bf16 v[40:43], v[174:177], v[204:207], v[40:43]
	v_mfma_f32_16x16x32_bf16 v[32:35], v[188:191], v[204:207], v[32:35]
	v_mfma_f32_16x16x32_bf16 v[24:27], v[174:177], v[212:215], v[24:27]
	v_mfma_f32_16x16x32_bf16 v[16:19], v[188:191], v[212:215], v[16:19]
	s_setprio 3
	s_barrier
	v_mfma_f32_16x16x32_bf16 v[8:11], v[174:177], v[220:223], v[8:11]
	v_mfma_f32_16x16x32_bf16 v[0:3], v[188:191], v[220:223], v[0:3]
	s_setprio 0
	s_add_i32 s51, 0, 0x18000
	s_add_i32 s52, 0, 0x1c000
	v_add_u32_e32 v166, s51, v145
	v_add_u32_e32 v180, s52, v145
	ds_read_b128 v[154:157], v166
	ds_read_b128 v[158:161], v166 offset:1024
	ds_read_b128 v[162:165], v166 offset:2048
	ds_read_b128 v[166:169], v166 offset:3072
	ds_read_b128 v[170:173], v180
	ds_read_b128 v[174:177], v180 offset:1024
	ds_read_b128 v[184:187], v180 offset:2048
	ds_read_b128 v[188:191], v180 offset:3072
	v_lshl_add_u64 v[226:227], s[24:25], 0, v[134:135]
	s_mov_b32 m0, s19
	v_lshl_add_u64 v[228:229], s[24:25], 0, v[130:131]
	global_load_lds_dwordx4 v[226:227], off
	s_mov_b32 m0, s30
	s_nop 0
	global_load_lds_dwordx4 v[228:229], off
	s_add_u32 s24, s24, 0x40000
	s_addc_u32 s25, s25, 0
	s_mov_b32 m0, s31
	v_lshl_add_u64 v[230:231], s[24:25], 0, v[134:135]
	ds_read_b128 v[192:195], v153 offset:32768
	ds_read_b128 v[196:199], v153 offset:33792
	ds_read_b128 v[200:203], v153 offset:34816
	ds_read_b128 v[204:207], v153 offset:35840
	ds_read_b128 v[208:211], v153 offset:36864
	ds_read_b128 v[212:215], v153 offset:37888
	ds_read_b128 v[216:219], v153 offset:38912
	ds_read_b128 v[220:223], v153 offset:39936
	global_load_lds_dwordx4 v[230:231], off
	v_lshl_add_u64 v[230:231], s[24:25], 0, v[130:131]
	s_mov_b32 m0, s33
	s_nop 0
	global_load_lds_dwordx4 v[230:231], off
	s_waitcnt vmcnt(8)
	s_waitcnt lgkmcnt(0)
	s_barrier
	s_waitcnt lgkmcnt(0)
	v_mfma_f32_16x16x32_bf16 v[124:127], v[154:157], v[192:195], v[124:127]
	v_mfma_f32_16x16x32_bf16 v[116:119], v[162:165], v[192:195], v[116:119]
	v_mfma_f32_16x16x32_bf16 v[108:111], v[154:157], v[200:203], v[108:111]
	v_mfma_f32_16x16x32_bf16 v[100:103], v[162:165], v[200:203], v[100:103]
	v_mfma_f32_16x16x32_bf16 v[92:95], v[154:157], v[208:211], v[92:95]
	v_mfma_f32_16x16x32_bf16 v[84:87], v[162:165], v[208:211], v[84:87]
	v_mfma_f32_16x16x32_bf16 v[76:79], v[154:157], v[216:219], v[76:79]
	v_mfma_f32_16x16x32_bf16 v[68:71], v[162:165], v[216:219], v[68:71]
	v_mfma_f32_16x16x32_bf16 v[124:127], v[158:161], v[196:199], v[124:127]
	v_mfma_f32_16x16x32_bf16 v[116:119], v[166:169], v[196:199], v[116:119]
	v_mfma_f32_16x16x32_bf16 v[108:111], v[158:161], v[204:207], v[108:111]
	v_mfma_f32_16x16x32_bf16 v[100:103], v[166:169], v[204:207], v[100:103]
	v_mfma_f32_16x16x32_bf16 v[92:95], v[158:161], v[212:215], v[92:95]
	v_mfma_f32_16x16x32_bf16 v[84:87], v[166:169], v[212:215], v[84:87]
	v_mfma_f32_16x16x32_bf16 v[76:79], v[158:161], v[220:223], v[76:79]
	v_mfma_f32_16x16x32_bf16 v[68:71], v[166:169], v[220:223], v[68:71]
	v_mfma_f32_16x16x32_bf16 v[120:123], v[170:173], v[192:195], v[120:123]
	v_mfma_f32_16x16x32_bf16 v[112:115], v[184:187], v[192:195], v[112:115]
	v_mfma_f32_16x16x32_bf16 v[104:107], v[170:173], v[200:203], v[104:107]
	v_mfma_f32_16x16x32_bf16 v[96:99], v[184:187], v[200:203], v[96:99]
	v_mfma_f32_16x16x32_bf16 v[88:91], v[170:173], v[208:211], v[88:91]
	v_mfma_f32_16x16x32_bf16 v[80:83], v[184:187], v[208:211], v[80:83]
	v_mfma_f32_16x16x32_bf16 v[72:75], v[170:173], v[216:219], v[72:75]
	v_mfma_f32_16x16x32_bf16 v[64:67], v[184:187], v[216:219], v[64:67]
	v_mfma_f32_16x16x32_bf16 v[120:123], v[174:177], v[196:199], v[120:123]
	v_mfma_f32_16x16x32_bf16 v[112:115], v[188:191], v[196:199], v[112:115]
	v_mfma_f32_16x16x32_bf16 v[104:107], v[174:177], v[204:207], v[104:107]
	v_mfma_f32_16x16x32_bf16 v[96:99], v[188:191], v[204:207], v[96:99]
	v_mfma_f32_16x16x32_bf16 v[88:91], v[174:177], v[212:215], v[88:91]
	v_mfma_f32_16x16x32_bf16 v[80:83], v[188:191], v[212:215], v[80:83]
	s_setprio 3
	s_barrier
	v_mfma_f32_16x16x32_bf16 v[72:75], v[174:177], v[220:223], v[72:75]
	v_mfma_f32_16x16x32_bf16 v[64:67], v[188:191], v[220:223], v[64:67]
	s_setprio 0
	s_add_i32 s24, s51, s28
	v_lshl_add_u64 v[178:179], v[178:179], 0, s[6:7]
	s_mov_b32 m0, s24
	ds_read_b128 v[192:195], v153 offset:49152
	ds_read_b128 v[196:199], v153 offset:50176
	ds_read_b128 v[200:203], v153 offset:51200
	ds_read_b128 v[204:207], v153 offset:52224
	ds_read_b128 v[208:211], v153 offset:53248
	ds_read_b128 v[212:215], v153 offset:54272
	ds_read_b128 v[216:219], v153 offset:55296
	ds_read_b128 v[220:223], v153 offset:56320
	global_load_lds_dwordx4 v[178:179], off
	s_add_i32 m0, s24, 0x2000
	s_add_u32 s22, s22, 0x40080
	v_lshl_add_u64 v[178:179], v[224:225], 0, s[6:7]
	s_addc_u32 s23, s23, 0
	s_add_i32 s24, s52, s28
	global_load_lds_dwordx4 v[178:179], off
	v_lshl_add_u64 v[178:179], s[22:23], 0, v[132:133]
	s_mov_b32 m0, s24
	s_nop 0
	global_load_lds_dwordx4 v[178:179], off
	v_lshl_add_u64 v[178:179], s[22:23], 0, v[128:129]
	s_add_i32 m0, s24, 0x2000
	s_nop 0
	global_load_lds_dwordx4 v[178:179], off
	s_waitcnt vmcnt(6)
	s_waitcnt lgkmcnt(0)
	s_barrier
	s_waitcnt lgkmcnt(0)
	v_mfma_f32_16x16x32_bf16 v[60:63], v[154:157], v[192:195], v[60:63]
	v_mfma_f32_16x16x32_bf16 v[52:55], v[162:165], v[192:195], v[52:55]
	v_mfma_f32_16x16x32_bf16 v[44:47], v[154:157], v[200:203], v[44:47]
	v_mfma_f32_16x16x32_bf16 v[36:39], v[162:165], v[200:203], v[36:39]
	v_mfma_f32_16x16x32_bf16 v[28:31], v[154:157], v[208:211], v[28:31]
	v_mfma_f32_16x16x32_bf16 v[20:23], v[162:165], v[208:211], v[20:23]
	v_mfma_f32_16x16x32_bf16 v[12:15], v[154:157], v[216:219], v[12:15]
	v_mfma_f32_16x16x32_bf16 v[4:7], v[162:165], v[216:219], v[4:7]
	v_mfma_f32_16x16x32_bf16 v[60:63], v[158:161], v[196:199], v[60:63]
	v_mfma_f32_16x16x32_bf16 v[52:55], v[166:169], v[196:199], v[52:55]
	v_mfma_f32_16x16x32_bf16 v[44:47], v[158:161], v[204:207], v[44:47]
	v_mfma_f32_16x16x32_bf16 v[36:39], v[166:169], v[204:207], v[36:39]
	v_mfma_f32_16x16x32_bf16 v[28:31], v[158:161], v[212:215], v[28:31]
	v_mfma_f32_16x16x32_bf16 v[20:23], v[166:169], v[212:215], v[20:23]
	v_mfma_f32_16x16x32_bf16 v[12:15], v[158:161], v[220:223], v[12:15]
	v_mfma_f32_16x16x32_bf16 v[4:7], v[166:169], v[220:223], v[4:7]
	v_mfma_f32_16x16x32_bf16 v[56:59], v[170:173], v[192:195], v[56:59]
	v_mfma_f32_16x16x32_bf16 v[48:51], v[184:187], v[192:195], v[48:51]
	v_mfma_f32_16x16x32_bf16 v[40:43], v[170:173], v[200:203], v[40:43]
	v_mfma_f32_16x16x32_bf16 v[32:35], v[184:187], v[200:203], v[32:35]
	v_mfma_f32_16x16x32_bf16 v[24:27], v[170:173], v[208:211], v[24:27]
	v_mfma_f32_16x16x32_bf16 v[16:19], v[184:187], v[208:211], v[16:19]
	v_mfma_f32_16x16x32_bf16 v[8:11], v[170:173], v[216:219], v[8:11]
	v_mfma_f32_16x16x32_bf16 v[0:3], v[184:187], v[216:219], v[0:3]
	v_mfma_f32_16x16x32_bf16 v[56:59], v[174:177], v[196:199], v[56:59]
	v_mfma_f32_16x16x32_bf16 v[48:51], v[188:191], v[196:199], v[48:51]
	v_mfma_f32_16x16x32_bf16 v[40:43], v[174:177], v[204:207], v[40:43]
	v_mfma_f32_16x16x32_bf16 v[32:35], v[188:191], v[204:207], v[32:35]
	v_mfma_f32_16x16x32_bf16 v[24:27], v[174:177], v[212:215], v[24:27]
	v_mfma_f32_16x16x32_bf16 v[16:19], v[188:191], v[212:215], v[16:19]
	s_setprio 3
	s_barrier
	v_mfma_f32_16x16x32_bf16 v[8:11], v[174:177], v[220:223], v[8:11]
	v_mfma_f32_16x16x32_bf16 v[0:3], v[188:191], v[220:223], v[0:3]
	s_setprio 0
	v_lshl_add_u64 v[178:179], v[226:227], 0, s[6:7]
	s_mov_b32 m0, s34
	s_nop 0
	global_load_lds_dwordx4 v[178:179], off
	v_lshl_add_u64 v[178:179], v[228:229], 0, s[6:7]
	s_mov_b32 m0, s35
	s_nop 0
	global_load_lds_dwordx4 v[178:179], off
	s_add_i32 s50, s50, 2
	s_add_u32 s20, s20, 0x100
	s_addc_u32 s21, s21, 0
	s_add_u32 s46, s46, 0x100
	s_addc_u32 s47, s47, 0
	s_cmp_gt_u32 s50, 13

.LBB0_786:
	s_add_u32 s43, s20, 0x100
	s_addc_u32 s46, s21, 0
	s_mov_b32 s47, -2
	s_waitcnt lgkmcnt(0)
	ds_read_b128 v[144:147], v151
	ds_read_b128 v[156:159], v151 offset:1024
	ds_read_b128 v[160:163], v151 offset:2048
	ds_read_b128 v[164:167], v151 offset:3072
	ds_read_b128 v[168:171], v152
	ds_read_b128 v[172:175], v152 offset:1024
	ds_read_b128 v[176:179], v152 offset:2048
	ds_read_b128 v[184:187], v152 offset:3072
	s_add_u32 s20, s18, 0x100
	s_addc_u32 s21, s19, 0
	s_cmp_eq_u32 s47, 40
	s_cselect_b32 s25, s7, s21
	s_cselect_b32 s24, s6, s20
	s_cselect_b32 s23, s17, s46
	s_cselect_b32 s22, s16, s43
	v_lshl_add_u64 v[220:221], s[18:19], 0, v[136:137]
	s_add_i32 m0, s29, 0xc000
	ds_read_b128 v[188:191], v153
	ds_read_b128 v[192:195], v153 offset:1024
	ds_read_b128 v[196:199], v153 offset:2048
	ds_read_b128 v[200:203], v153 offset:3072
	ds_read_b128 v[204:207], v153 offset:4096
	ds_read_b128 v[208:211], v153 offset:5120
	ds_read_b128 v[212:215], v153 offset:6144
	ds_read_b128 v[216:219], v153 offset:7168
	global_load_lds_dwordx4 v[220:221], off
	v_lshl_add_u64 v[220:221], s[18:19], 0, v[138:139]
	s_add_i32 m0, s29, 0xe000
	s_nop 0
	global_load_lds_dwordx4 v[220:221], off
	s_waitcnt vmcnt(8)
	s_waitcnt lgkmcnt(0)
	s_barrier
	s_waitcnt lgkmcnt(0)
	v_mfma_f32_16x16x32_bf16 v[124:127], v[144:147], v[188:191], 0
	v_mfma_f32_16x16x32_bf16 v[120:123], v[160:163], v[188:191], 0
	v_mfma_f32_16x16x32_bf16 v[108:111], v[144:147], v[196:199], 0
	v_mfma_f32_16x16x32_bf16 v[104:107], v[160:163], v[196:199], 0
	v_mfma_f32_16x16x32_bf16 v[92:95], v[144:147], v[204:207], 0
	v_mfma_f32_16x16x32_bf16 v[88:91], v[160:163], v[204:207], 0
	v_mfma_f32_16x16x32_bf16 v[76:79], v[144:147], v[212:215], 0
	v_mfma_f32_16x16x32_bf16 v[72:75], v[160:163], v[212:215], 0
	v_mfma_f32_16x16x32_bf16 v[124:127], v[156:159], v[192:195], v[124:127]
	v_mfma_f32_16x16x32_bf16 v[120:123], v[164:167], v[192:195], v[120:123]
	v_mfma_f32_16x16x32_bf16 v[108:111], v[156:159], v[200:203], v[108:111]
	v_mfma_f32_16x16x32_bf16 v[104:107], v[164:167], v[200:203], v[104:107]
	v_mfma_f32_16x16x32_bf16 v[92:95], v[156:159], v[208:211], v[92:95]
	v_mfma_f32_16x16x32_bf16 v[88:91], v[164:167], v[208:211], v[88:91]
	v_mfma_f32_16x16x32_bf16 v[76:79], v[156:159], v[216:219], v[76:79]
	v_mfma_f32_16x16x32_bf16 v[72:75], v[164:167], v[216:219], v[72:75]
	v_mfma_f32_16x16x32_bf16 v[116:119], v[168:171], v[188:191], 0
	v_mfma_f32_16x16x32_bf16 v[112:115], v[176:179], v[188:191], 0
	v_mfma_f32_16x16x32_bf16 v[100:103], v[168:171], v[196:199], 0
	v_mfma_f32_16x16x32_bf16 v[96:99], v[176:179], v[196:199], 0
	v_mfma_f32_16x16x32_bf16 v[84:87], v[168:171], v[204:207], 0
	v_mfma_f32_16x16x32_bf16 v[80:83], v[176:179], v[204:207], 0
	v_mfma_f32_16x16x32_bf16 v[68:71], v[168:171], v[212:215], 0
	v_mfma_f32_16x16x32_bf16 v[64:67], v[176:179], v[212:215], 0
	v_mfma_f32_16x16x32_bf16 v[116:119], v[172:175], v[192:195], v[116:119]
	v_mfma_f32_16x16x32_bf16 v[112:115], v[184:187], v[192:195], v[112:115]
	v_mfma_f32_16x16x32_bf16 v[100:103], v[172:175], v[200:203], v[100:103]
	v_mfma_f32_16x16x32_bf16 v[96:99], v[184:187], v[200:203], v[96:99]
	v_mfma_f32_16x16x32_bf16 v[84:87], v[172:175], v[208:211], v[84:87]
	v_mfma_f32_16x16x32_bf16 v[80:83], v[184:187], v[208:211], v[80:83]
	s_setprio 3
	s_barrier
	v_mfma_f32_16x16x32_bf16 v[68:71], v[172:175], v[216:219], v[68:71]
	v_mfma_f32_16x16x32_bf16 v[64:67], v[184:187], v[216:219], v[64:67]
	s_setprio 0
	s_add_i32 s18, s37, s28
	v_lshl_add_u64 v[220:221], s[22:23], 0, v[130:131]
	s_mov_b32 m0, s18
	ds_read_b128 v[188:191], v153 offset:16384
	ds_read_b128 v[192:195], v153 offset:17408
	ds_read_b128 v[196:199], v153 offset:18432
	ds_read_b128 v[200:203], v153 offset:19456
	ds_read_b128 v[204:207], v153 offset:20480
	ds_read_b128 v[208:211], v153 offset:21504
	ds_read_b128 v[212:215], v153 offset:22528
	ds_read_b128 v[216:219], v153 offset:23552
	global_load_lds_dwordx4 v[220:221], off
	s_add_i32 m0, s18, 0x2000
	s_add_u32 s18, s22, 0xb0000
	v_lshl_add_u64 v[222:223], s[22:23], 0, v[134:135]
	s_addc_u32 s19, s23, 0
	s_add_i32 s50, s38, s28
	global_load_lds_dwordx4 v[222:223], off
	v_lshl_add_u64 v[224:225], s[18:19], 0, v[130:131]
	s_mov_b32 m0, s50
	global_load_lds_dwordx4 v[224:225], off
	v_lshl_add_u64 v[224:225], s[18:19], 0, v[134:135]
	s_add_i32 m0, s50, 0x2000
	s_nop 0
	global_load_lds_dwordx4 v[224:225], off
	s_waitcnt vmcnt(6)
	s_waitcnt lgkmcnt(0)
	s_barrier
	s_waitcnt lgkmcnt(0)
	v_mfma_f32_16x16x32_bf16 v[60:63], v[144:147], v[188:191], 0
	v_mfma_f32_16x16x32_bf16 v[56:59], v[160:163], v[188:191], 0
	v_mfma_f32_16x16x32_bf16 v[44:47], v[144:147], v[196:199], 0
	v_mfma_f32_16x16x32_bf16 v[40:43], v[160:163], v[196:199], 0
	v_mfma_f32_16x16x32_bf16 v[28:31], v[144:147], v[204:207], 0
	v_mfma_f32_16x16x32_bf16 v[24:27], v[160:163], v[204:207], 0
	v_mfma_f32_16x16x32_bf16 v[12:15], v[144:147], v[212:215], 0
	v_mfma_f32_16x16x32_bf16 v[8:11], v[160:163], v[212:215], 0
	v_mfma_f32_16x16x32_bf16 v[60:63], v[156:159], v[192:195], v[60:63]
	v_mfma_f32_16x16x32_bf16 v[56:59], v[164:167], v[192:195], v[56:59]
	v_mfma_f32_16x16x32_bf16 v[44:47], v[156:159], v[200:203], v[44:47]
	v_mfma_f32_16x16x32_bf16 v[40:43], v[164:167], v[200:203], v[40:43]
	v_mfma_f32_16x16x32_bf16 v[28:31], v[156:159], v[208:211], v[28:31]
	v_mfma_f32_16x16x32_bf16 v[24:27], v[164:167], v[208:211], v[24:27]
	v_mfma_f32_16x16x32_bf16 v[12:15], v[156:159], v[216:219], v[12:15]
	v_mfma_f32_16x16x32_bf16 v[8:11], v[164:167], v[216:219], v[8:11]
	v_mfma_f32_16x16x32_bf16 v[52:55], v[168:171], v[188:191], 0
	v_mfma_f32_16x16x32_bf16 v[48:51], v[176:179], v[188:191], 0
	v_mfma_f32_16x16x32_bf16 v[36:39], v[168:171], v[196:199], 0
	v_mfma_f32_16x16x32_bf16 v[32:35], v[176:179], v[196:199], 0
	v_mfma_f32_16x16x32_bf16 v[20:23], v[168:171], v[204:207], 0
	v_mfma_f32_16x16x32_bf16 v[16:19], v[176:179], v[204:207], 0
	v_mfma_f32_16x16x32_bf16 v[4:7], v[168:171], v[212:215], 0
	v_mfma_f32_16x16x32_bf16 v[0:3], v[176:179], v[212:215], 0
	v_mfma_f32_16x16x32_bf16 v[52:55], v[172:175], v[192:195], v[52:55]
	v_mfma_f32_16x16x32_bf16 v[48:51], v[184:187], v[192:195], v[48:51]
	v_mfma_f32_16x16x32_bf16 v[36:39], v[172:175], v[200:203], v[36:39]
	v_mfma_f32_16x16x32_bf16 v[32:35], v[184:187], v[200:203], v[32:35]
	v_mfma_f32_16x16x32_bf16 v[20:23], v[172:175], v[208:211], v[20:23]
	v_mfma_f32_16x16x32_bf16 v[16:19], v[184:187], v[208:211], v[16:19]
	s_setprio 3
	s_barrier
	v_mfma_f32_16x16x32_bf16 v[4:7], v[172:175], v[216:219], v[4:7]
	v_mfma_f32_16x16x32_bf16 v[0:3], v[184:187], v[216:219], v[0:3]
	s_setprio 0
	s_add_i32 s50, 0, 0x18000
	v_add_u32_e32 v155, s50, v149
	s_add_i32 s51, 0, 0x1c000
	ds_read_b128 v[144:147], v155
	ds_read_b128 v[156:159], v155 offset:1024
	ds_read_b128 v[160:163], v155 offset:2048
	ds_read_b128 v[164:167], v155 offset:3072
	v_add_u32_e32 v155, s51, v149
	ds_read_b128 v[168:171], v155
	ds_read_b128 v[172:175], v155 offset:1024
	ds_read_b128 v[176:179], v155 offset:2048
	ds_read_b128 v[184:187], v155 offset:3072
	s_add_u32 s18, s24, 0xb0000
	s_addc_u32 s19, s25, 0
	v_lshl_add_u64 v[224:225], s[24:25], 0, v[128:129]
	s_mov_b32 m0, s29
	v_lshl_add_u64 v[226:227], s[24:25], 0, v[132:133]
	global_load_lds_dwordx4 v[224:225], off
	s_mov_b32 m0, s30
	s_nop 0
	global_load_lds_dwordx4 v[226:227], off
	s_mov_b32 m0, s31
	v_lshl_add_u64 v[228:229], s[18:19], 0, v[128:129]
	ds_read_b128 v[188:191], v153 offset:32768
	ds_read_b128 v[192:195], v153 offset:33792
	ds_read_b128 v[196:199], v153 offset:34816
	ds_read_b128 v[200:203], v153 offset:35840
	ds_read_b128 v[204:207], v153 offset:36864
	ds_read_b128 v[208:211], v153 offset:37888
	ds_read_b128 v[212:215], v153 offset:38912
	ds_read_b128 v[216:219], v153 offset:39936
	global_load_lds_dwordx4 v[228:229], off
	v_lshl_add_u64 v[228:229], s[18:19], 0, v[132:133]
	s_mov_b32 m0, s33
	s_nop 0
	global_load_lds_dwordx4 v[228:229], off
	s_waitcnt vmcnt(8)
	s_waitcnt lgkmcnt(0)
	s_barrier
	s_waitcnt lgkmcnt(0)
	v_mfma_f32_16x16x32_bf16 v[124:127], v[144:147], v[188:191], v[124:127]
	v_mfma_f32_16x16x32_bf16 v[120:123], v[160:163], v[188:191], v[120:123]
	v_mfma_f32_16x16x32_bf16 v[108:111], v[144:147], v[196:199], v[108:111]
	v_mfma_f32_16x16x32_bf16 v[104:107], v[160:163], v[196:199], v[104:107]
	v_mfma_f32_16x16x32_bf16 v[92:95], v[144:147], v[204:207], v[92:95]
	v_mfma_f32_16x16x32_bf16 v[88:91], v[160:163], v[204:207], v[88:91]
	v_mfma_f32_16x16x32_bf16 v[76:79], v[144:147], v[212:215], v[76:79]
	v_mfma_f32_16x16x32_bf16 v[72:75], v[160:163], v[212:215], v[72:75]
	v_mfma_f32_16x16x32_bf16 v[124:127], v[156:159], v[192:195], v[124:127]
	v_mfma_f32_16x16x32_bf16 v[120:123], v[164:167], v[192:195], v[120:123]
	v_mfma_f32_16x16x32_bf16 v[108:111], v[156:159], v[200:203], v[108:111]
	v_mfma_f32_16x16x32_bf16 v[104:107], v[164:167], v[200:203], v[104:107]
	v_mfma_f32_16x16x32_bf16 v[92:95], v[156:159], v[208:211], v[92:95]
	v_mfma_f32_16x16x32_bf16 v[88:91], v[164:167], v[208:211], v[88:91]
	v_mfma_f32_16x16x32_bf16 v[76:79], v[156:159], v[216:219], v[76:79]
	v_mfma_f32_16x16x32_bf16 v[72:75], v[164:167], v[216:219], v[72:75]
	v_mfma_f32_16x16x32_bf16 v[116:119], v[168:171], v[188:191], v[116:119]
	v_mfma_f32_16x16x32_bf16 v[112:115], v[176:179], v[188:191], v[112:115]
	v_mfma_f32_16x16x32_bf16 v[100:103], v[168:171], v[196:199], v[100:103]
	v_mfma_f32_16x16x32_bf16 v[96:99], v[176:179], v[196:199], v[96:99]
	v_mfma_f32_16x16x32_bf16 v[84:87], v[168:171], v[204:207], v[84:87]
	v_mfma_f32_16x16x32_bf16 v[80:83], v[176:179], v[204:207], v[80:83]
	v_mfma_f32_16x16x32_bf16 v[68:71], v[168:171], v[212:215], v[68:71]
	v_mfma_f32_16x16x32_bf16 v[64:67], v[176:179], v[212:215], v[64:67]
	v_mfma_f32_16x16x32_bf16 v[116:119], v[172:175], v[192:195], v[116:119]
	v_mfma_f32_16x16x32_bf16 v[112:115], v[184:187], v[192:195], v[112:115]
	v_mfma_f32_16x16x32_bf16 v[100:103], v[172:175], v[200:203], v[100:103]
	v_mfma_f32_16x16x32_bf16 v[96:99], v[184:187], v[200:203], v[96:99]
	v_mfma_f32_16x16x32_bf16 v[84:87], v[172:175], v[208:211], v[84:87]
	v_mfma_f32_16x16x32_bf16 v[80:83], v[184:187], v[208:211], v[80:83]
	s_setprio 3
	s_barrier
	v_mfma_f32_16x16x32_bf16 v[68:71], v[172:175], v[216:219], v[68:71]
	v_mfma_f32_16x16x32_bf16 v[64:67], v[184:187], v[216:219], v[64:67]
	s_setprio 0
	s_add_i32 s18, s50, s28
	v_lshl_add_u64 v[220:221], v[220:221], 0, s[12:13]
	s_mov_b32 m0, s18
	ds_read_b128 v[188:191], v153 offset:49152
	ds_read_b128 v[192:195], v153 offset:50176
	ds_read_b128 v[196:199], v153 offset:51200
	ds_read_b128 v[200:203], v153 offset:52224
	ds_read_b128 v[204:207], v153 offset:53248
	ds_read_b128 v[208:211], v153 offset:54272
	ds_read_b128 v[212:215], v153 offset:55296
	ds_read_b128 v[216:219], v153 offset:56320
	global_load_lds_dwordx4 v[220:221], off
	s_add_i32 m0, s18, 0x2000
	s_add_u32 s18, s22, 0xb0080
	v_lshl_add_u64 v[220:221], v[222:223], 0, s[12:13]
	s_addc_u32 s19, s23, 0
	s_add_i32 s22, s51, s28
	global_load_lds_dwordx4 v[220:221], off
	v_lshl_add_u64 v[220:221], s[18:19], 0, v[130:131]
	s_mov_b32 m0, s22
	s_nop 0
	global_load_lds_dwordx4 v[220:221], off
	v_lshl_add_u64 v[220:221], s[18:19], 0, v[134:135]
	s_add_i32 m0, s22, 0x2000
	s_nop 0
	global_load_lds_dwordx4 v[220:221], off
	s_waitcnt vmcnt(6)
	s_waitcnt lgkmcnt(0)
	s_barrier
	s_waitcnt lgkmcnt(0)
	v_mfma_f32_16x16x32_bf16 v[60:63], v[144:147], v[188:191], v[60:63]
	v_mfma_f32_16x16x32_bf16 v[56:59], v[160:163], v[188:191], v[56:59]
	v_mfma_f32_16x16x32_bf16 v[44:47], v[144:147], v[196:199], v[44:47]
	v_mfma_f32_16x16x32_bf16 v[40:43], v[160:163], v[196:199], v[40:43]
	v_mfma_f32_16x16x32_bf16 v[28:31], v[144:147], v[204:207], v[28:31]
	v_mfma_f32_16x16x32_bf16 v[24:27], v[160:163], v[204:207], v[24:27]
	v_mfma_f32_16x16x32_bf16 v[12:15], v[144:147], v[212:215], v[12:15]
	v_mfma_f32_16x16x32_bf16 v[8:11], v[160:163], v[212:215], v[8:11]
	v_mfma_f32_16x16x32_bf16 v[60:63], v[156:159], v[192:195], v[60:63]
	v_mfma_f32_16x16x32_bf16 v[56:59], v[164:167], v[192:195], v[56:59]
	v_mfma_f32_16x16x32_bf16 v[44:47], v[156:159], v[200:203], v[44:47]
	v_mfma_f32_16x16x32_bf16 v[40:43], v[164:167], v[200:203], v[40:43]
	v_mfma_f32_16x16x32_bf16 v[28:31], v[156:159], v[208:211], v[28:31]
	v_mfma_f32_16x16x32_bf16 v[24:27], v[164:167], v[208:211], v[24:27]
	v_mfma_f32_16x16x32_bf16 v[12:15], v[156:159], v[216:219], v[12:15]
	v_mfma_f32_16x16x32_bf16 v[8:11], v[164:167], v[216:219], v[8:11]
	v_mfma_f32_16x16x32_bf16 v[52:55], v[168:171], v[188:191], v[52:55]
	v_mfma_f32_16x16x32_bf16 v[48:51], v[176:179], v[188:191], v[48:51]
	v_mfma_f32_16x16x32_bf16 v[36:39], v[168:171], v[196:199], v[36:39]
	v_mfma_f32_16x16x32_bf16 v[32:35], v[176:179], v[196:199], v[32:35]
	v_mfma_f32_16x16x32_bf16 v[20:23], v[168:171], v[204:207], v[20:23]
	v_mfma_f32_16x16x32_bf16 v[16:19], v[176:179], v[204:207], v[16:19]
	v_mfma_f32_16x16x32_bf16 v[4:7], v[168:171], v[212:215], v[4:7]
	v_mfma_f32_16x16x32_bf16 v[0:3], v[176:179], v[212:215], v[0:3]
	v_mfma_f32_16x16x32_bf16 v[52:55], v[172:175], v[192:195], v[52:55]
	v_mfma_f32_16x16x32_bf16 v[48:51], v[184:187], v[192:195], v[48:51]
	v_mfma_f32_16x16x32_bf16 v[36:39], v[172:175], v[200:203], v[36:39]
	v_mfma_f32_16x16x32_bf16 v[32:35], v[184:187], v[200:203], v[32:35]
	v_mfma_f32_16x16x32_bf16 v[20:23], v[172:175], v[208:211], v[20:23]
	v_mfma_f32_16x16x32_bf16 v[16:19], v[184:187], v[208:211], v[16:19]
	s_setprio 3
	s_barrier
	v_mfma_f32_16x16x32_bf16 v[4:7], v[172:175], v[216:219], v[4:7]
	v_mfma_f32_16x16x32_bf16 v[0:3], v[184:187], v[216:219], v[0:3]
	s_setprio 0
	v_lshl_add_u64 v[220:221], v[224:225], 0, s[12:13]
	s_mov_b32 m0, s35
	s_nop 0
	global_load_lds_dwordx4 v[220:221], off
	v_lshl_add_u64 v[220:221], v[226:227], 0, s[12:13]
	s_mov_b32 m0, s36
	s_nop 0
	global_load_lds_dwordx4 v[220:221], off
	s_add_i32 s47, s47, 2
	s_add_u32 s43, s43, 0x100
	s_addc_u32 s46, s46, 0
	s_cmp_gt_u32 s47, 41
	s_mov_b64 s[18:19], s[20:21]

.LBB0_876:
	s_ashr_i32 s23, s22, 31
	s_lshl_b64 s[24:25], s[22:23], 19
	s_add_u32 s24, s74, s24
	s_addc_u32 s25, s75, s25
	s_and_b64 s[26:27], s[6:7], exec
	s_cselect_b32 s11, s25, s29
	s_cselect_b32 s23, s24, s28
	s_ashr_i32 s21, s20, 31
	s_lshl_b64 s[26:27], s[20:21], 19
	s_add_u32 s26, s33, s26
	s_addc_u32 s27, s36, s27
	s_and_b64 s[34:35], s[6:7], exec
	s_cselect_b32 s21, s27, s31
	s_cselect_b32 s53, s26, s30
	s_add_u32 s28, s28, 0x40080
	s_addc_u32 s29, s29, 0
	s_add_u32 s54, s30, 0x100
	s_addc_u32 s55, s31, 0
	s_mov_b32 s56, -2
	s_waitcnt lgkmcnt(0)
	ds_read_b128 v[144:147], v173
	ds_read_b128 v[148:151], v173 offset:1024
	ds_read_b128 v[152:155], v173 offset:2048
	ds_read_b128 v[156:159], v173 offset:3072
	ds_read_b128 v[184:187], v174
	ds_read_b128 v[188:191], v174 offset:1024
	ds_read_b128 v[192:195], v174 offset:2048
	ds_read_b128 v[196:199], v174 offset:3072
	s_add_u32 s30, s28, 0xfffc0080
	s_addc_u32 s31, s29, -1
	s_cmp_eq_u32 s56, 12
	s_cselect_b32 s35, s11, s31
	s_cselect_b32 s34, s23, s30
	s_cselect_b32 s31, s21, s55
	s_cselect_b32 s30, s53, s54
	v_lshl_add_u64 v[160:161], s[28:29], 0, v[136:137]
	s_add_i32 m0, s38, 0xc000
	ds_read_b128 v[200:203], v175
	ds_read_b128 v[204:207], v175 offset:1024
	ds_read_b128 v[208:211], v175 offset:2048
	ds_read_b128 v[212:215], v175 offset:3072
	ds_read_b128 v[216:219], v175 offset:4096
	ds_read_b128 v[220:223], v175 offset:5120
	ds_read_b128 v[224:227], v175 offset:6144
	ds_read_b128 v[228:231], v175 offset:7168
	global_load_lds_dwordx4 v[160:161], off
	v_lshl_add_u64 v[160:161], s[28:29], 0, v[138:139]
	s_add_i32 m0, s38, 0xe000
	s_nop 0
	global_load_lds_dwordx4 v[160:161], off
	s_waitcnt vmcnt(8)
	s_waitcnt lgkmcnt(0)
	s_barrier
	s_waitcnt lgkmcnt(0)
	v_mfma_f32_16x16x32_bf16 v[124:127], v[144:147], v[200:203], 0
	v_mfma_f32_16x16x32_bf16 v[120:123], v[152:155], v[200:203], 0
	v_mfma_f32_16x16x32_bf16 v[108:111], v[144:147], v[208:211], 0
	v_mfma_f32_16x16x32_bf16 v[104:107], v[152:155], v[208:211], 0
	v_mfma_f32_16x16x32_bf16 v[92:95], v[144:147], v[216:219], 0
	v_mfma_f32_16x16x32_bf16 v[88:91], v[152:155], v[216:219], 0
	v_mfma_f32_16x16x32_bf16 v[76:79], v[144:147], v[224:227], 0
	v_mfma_f32_16x16x32_bf16 v[72:75], v[152:155], v[224:227], 0
	v_mfma_f32_16x16x32_bf16 v[124:127], v[148:151], v[204:207], v[124:127]
	v_mfma_f32_16x16x32_bf16 v[120:123], v[156:159], v[204:207], v[120:123]
	v_mfma_f32_16x16x32_bf16 v[108:111], v[148:151], v[212:215], v[108:111]
	v_mfma_f32_16x16x32_bf16 v[104:107], v[156:159], v[212:215], v[104:107]
	v_mfma_f32_16x16x32_bf16 v[92:95], v[148:151], v[220:223], v[92:95]
	v_mfma_f32_16x16x32_bf16 v[88:91], v[156:159], v[220:223], v[88:91]
	v_mfma_f32_16x16x32_bf16 v[76:79], v[148:151], v[228:231], v[76:79]
	v_mfma_f32_16x16x32_bf16 v[72:75], v[156:159], v[228:231], v[72:75]
	v_mfma_f32_16x16x32_bf16 v[116:119], v[184:187], v[200:203], 0
	v_mfma_f32_16x16x32_bf16 v[112:115], v[192:195], v[200:203], 0
	v_mfma_f32_16x16x32_bf16 v[100:103], v[184:187], v[208:211], 0
	v_mfma_f32_16x16x32_bf16 v[96:99], v[192:195], v[208:211], 0
	v_mfma_f32_16x16x32_bf16 v[84:87], v[184:187], v[216:219], 0
	v_mfma_f32_16x16x32_bf16 v[80:83], v[192:195], v[216:219], 0
	v_mfma_f32_16x16x32_bf16 v[68:71], v[184:187], v[224:227], 0
	v_mfma_f32_16x16x32_bf16 v[64:67], v[192:195], v[224:227], 0
	v_mfma_f32_16x16x32_bf16 v[116:119], v[188:191], v[204:207], v[116:119]
	v_mfma_f32_16x16x32_bf16 v[112:115], v[196:199], v[204:207], v[112:115]
	v_mfma_f32_16x16x32_bf16 v[100:103], v[188:191], v[212:215], v[100:103]
	v_mfma_f32_16x16x32_bf16 v[96:99], v[196:199], v[212:215], v[96:99]
	v_mfma_f32_16x16x32_bf16 v[84:87], v[188:191], v[220:223], v[84:87]
	v_mfma_f32_16x16x32_bf16 v[80:83], v[196:199], v[220:223], v[80:83]
	s_setprio 3
	s_barrier
	v_mfma_f32_16x16x32_bf16 v[68:71], v[188:191], v[228:231], v[68:71]
	v_mfma_f32_16x16x32_bf16 v[64:67], v[196:199], v[228:231], v[64:67]
	s_setprio 0
	s_add_i32 s57, s47, s37
	v_lshl_add_u64 v[160:161], s[30:31], 0, v[130:131]
	s_mov_b32 m0, s57
	ds_read_b128 v[200:203], v175 offset:16384
	ds_read_b128 v[204:207], v175 offset:17408
	ds_read_b128 v[208:211], v175 offset:18432
	ds_read_b128 v[212:215], v175 offset:19456
	ds_read_b128 v[216:219], v175 offset:20480
	ds_read_b128 v[220:223], v175 offset:21504
	ds_read_b128 v[224:227], v175 offset:22528
	ds_read_b128 v[228:231], v175 offset:23552
	global_load_lds_dwordx4 v[160:161], off
	s_add_i32 m0, s57, 0x2000
	s_add_u32 s58, s30, 0x40000
	v_lshl_add_u64 v[178:179], s[30:31], 0, v[134:135]
	s_addc_u32 s59, s31, 0
	s_add_i32 s57, s50, s37
	global_load_lds_dwordx4 v[178:179], off
	v_lshl_add_u64 v[232:233], s[58:59], 0, v[130:131]
	s_mov_b32 m0, s57
	global_load_lds_dwordx4 v[232:233], off
	v_lshl_add_u64 v[232:233], s[58:59], 0, v[134:135]
	s_add_i32 m0, s57, 0x2000
	s_nop 0
	global_load_lds_dwordx4 v[232:233], off
	s_waitcnt vmcnt(6)
	s_waitcnt lgkmcnt(0)
	s_barrier
	s_waitcnt lgkmcnt(0)
	v_mfma_f32_16x16x32_bf16 v[60:63], v[144:147], v[200:203], 0
	v_mfma_f32_16x16x32_bf16 v[56:59], v[152:155], v[200:203], 0
	v_mfma_f32_16x16x32_bf16 v[44:47], v[144:147], v[208:211], 0
	v_mfma_f32_16x16x32_bf16 v[40:43], v[152:155], v[208:211], 0
	v_mfma_f32_16x16x32_bf16 v[28:31], v[144:147], v[216:219], 0
	v_mfma_f32_16x16x32_bf16 v[24:27], v[152:155], v[216:219], 0
	v_mfma_f32_16x16x32_bf16 v[12:15], v[144:147], v[224:227], 0
	v_mfma_f32_16x16x32_bf16 v[8:11], v[152:155], v[224:227], 0
	v_mfma_f32_16x16x32_bf16 v[60:63], v[148:151], v[204:207], v[60:63]
	v_mfma_f32_16x16x32_bf16 v[56:59], v[156:159], v[204:207], v[56:59]
	v_mfma_f32_16x16x32_bf16 v[44:47], v[148:151], v[212:215], v[44:47]
	v_mfma_f32_16x16x32_bf16 v[40:43], v[156:159], v[212:215], v[40:43]
	v_mfma_f32_16x16x32_bf16 v[28:31], v[148:151], v[220:223], v[28:31]
	v_mfma_f32_16x16x32_bf16 v[24:27], v[156:159], v[220:223], v[24:27]
	v_mfma_f32_16x16x32_bf16 v[12:15], v[148:151], v[228:231], v[12:15]
	v_mfma_f32_16x16x32_bf16 v[8:11], v[156:159], v[228:231], v[8:11]
	v_mfma_f32_16x16x32_bf16 v[52:55], v[184:187], v[200:203], 0
	v_mfma_f32_16x16x32_bf16 v[48:51], v[192:195], v[200:203], 0
	v_mfma_f32_16x16x32_bf16 v[36:39], v[184:187], v[208:211], 0
	v_mfma_f32_16x16x32_bf16 v[32:35], v[192:195], v[208:211], 0
	v_mfma_f32_16x16x32_bf16 v[20:23], v[184:187], v[216:219], 0
	v_mfma_f32_16x16x32_bf16 v[16:19], v[192:195], v[216:219], 0
	v_mfma_f32_16x16x32_bf16 v[4:7], v[184:187], v[224:227], 0
	v_mfma_f32_16x16x32_bf16 v[0:3], v[192:195], v[224:227], 0
	v_mfma_f32_16x16x32_bf16 v[52:55], v[188:191], v[204:207], v[52:55]
	v_mfma_f32_16x16x32_bf16 v[48:51], v[196:199], v[204:207], v[48:51]
	v_mfma_f32_16x16x32_bf16 v[36:39], v[188:191], v[212:215], v[36:39]
	v_mfma_f32_16x16x32_bf16 v[32:35], v[196:199], v[212:215], v[32:35]
	v_mfma_f32_16x16x32_bf16 v[20:23], v[188:191], v[220:223], v[20:23]
	v_mfma_f32_16x16x32_bf16 v[16:19], v[196:199], v[220:223], v[16:19]
	s_setprio 3
	s_barrier
	v_mfma_f32_16x16x32_bf16 v[4:7], v[188:191], v[228:231], v[4:7]
	v_mfma_f32_16x16x32_bf16 v[0:3], v[196:199], v[228:231], v[0:3]
	s_setprio 0
	s_add_i32 s57, 0, 0x18000
	s_add_i32 s58, 0, 0x1c000
	v_add_u32_e32 v156, s57, v163
	v_add_u32_e32 v177, s58, v163
	ds_read_b128 v[144:147], v156
	ds_read_b128 v[148:151], v156 offset:1024
	ds_read_b128 v[152:155], v156 offset:2048
	ds_read_b128 v[156:159], v156 offset:3072
	ds_read_b128 v[184:187], v177
	ds_read_b128 v[188:191], v177 offset:1024
	ds_read_b128 v[192:195], v177 offset:2048
	ds_read_b128 v[196:199], v177 offset:3072
	v_lshl_add_u64 v[232:233], s[34:35], 0, v[128:129]
	s_mov_b32 m0, s38
	v_lshl_add_u64 v[234:235], s[34:35], 0, v[132:133]
	global_load_lds_dwordx4 v[232:233], off
	s_mov_b32 m0, s39
	s_nop 0
	global_load_lds_dwordx4 v[234:235], off
	s_add_u32 s34, s34, 0x40000
	s_addc_u32 s35, s35, 0
	s_mov_b32 m0, s40
	v_lshl_add_u64 v[236:237], s[34:35], 0, v[128:129]
	ds_read_b128 v[200:203], v175 offset:32768
	ds_read_b128 v[204:207], v175 offset:33792
	ds_read_b128 v[208:211], v175 offset:34816
	ds_read_b128 v[212:215], v175 offset:35840
	ds_read_b128 v[216:219], v175 offset:36864
	ds_read_b128 v[220:223], v175 offset:37888
	ds_read_b128 v[224:227], v175 offset:38912
	ds_read_b128 v[228:231], v175 offset:39936
	global_load_lds_dwordx4 v[236:237], off
	v_lshl_add_u64 v[236:237], s[34:35], 0, v[132:133]
	s_mov_b32 m0, s41
	s_nop 0
	global_load_lds_dwordx4 v[236:237], off
	s_waitcnt vmcnt(8)
	s_waitcnt lgkmcnt(0)
	s_barrier
	s_waitcnt lgkmcnt(0)
	v_mfma_f32_16x16x32_bf16 v[124:127], v[144:147], v[200:203], v[124:127]
	v_mfma_f32_16x16x32_bf16 v[120:123], v[152:155], v[200:203], v[120:123]
	v_mfma_f32_16x16x32_bf16 v[108:111], v[144:147], v[208:211], v[108:111]
	v_mfma_f32_16x16x32_bf16 v[104:107], v[152:155], v[208:211], v[104:107]
	v_mfma_f32_16x16x32_bf16 v[92:95], v[144:147], v[216:219], v[92:95]
	v_mfma_f32_16x16x32_bf16 v[88:91], v[152:155], v[216:219], v[88:91]
	v_mfma_f32_16x16x32_bf16 v[76:79], v[144:147], v[224:227], v[76:79]
	v_mfma_f32_16x16x32_bf16 v[72:75], v[152:155], v[224:227], v[72:75]
	v_mfma_f32_16x16x32_bf16 v[124:127], v[148:151], v[204:207], v[124:127]
	v_mfma_f32_16x16x32_bf16 v[120:123], v[156:159], v[204:207], v[120:123]
	v_mfma_f32_16x16x32_bf16 v[108:111], v[148:151], v[212:215], v[108:111]
	v_mfma_f32_16x16x32_bf16 v[104:107], v[156:159], v[212:215], v[104:107]
	v_mfma_f32_16x16x32_bf16 v[92:95], v[148:151], v[220:223], v[92:95]
	v_mfma_f32_16x16x32_bf16 v[88:91], v[156:159], v[220:223], v[88:91]
	v_mfma_f32_16x16x32_bf16 v[76:79], v[148:151], v[228:231], v[76:79]
	v_mfma_f32_16x16x32_bf16 v[72:75], v[156:159], v[228:231], v[72:75]
	v_mfma_f32_16x16x32_bf16 v[116:119], v[184:187], v[200:203], v[116:119]
	v_mfma_f32_16x16x32_bf16 v[112:115], v[192:195], v[200:203], v[112:115]
	v_mfma_f32_16x16x32_bf16 v[100:103], v[184:187], v[208:211], v[100:103]
	v_mfma_f32_16x16x32_bf16 v[96:99], v[192:195], v[208:211], v[96:99]
	v_mfma_f32_16x16x32_bf16 v[84:87], v[184:187], v[216:219], v[84:87]
	v_mfma_f32_16x16x32_bf16 v[80:83], v[192:195], v[216:219], v[80:83]
	v_mfma_f32_16x16x32_bf16 v[68:71], v[184:187], v[224:227], v[68:71]
	v_mfma_f32_16x16x32_bf16 v[64:67], v[192:195], v[224:227], v[64:67]
	v_mfma_f32_16x16x32_bf16 v[116:119], v[188:191], v[204:207], v[116:119]
	v_mfma_f32_16x16x32_bf16 v[112:115], v[196:199], v[204:207], v[112:115]
	v_mfma_f32_16x16x32_bf16 v[100:103], v[188:191], v[212:215], v[100:103]
	v_mfma_f32_16x16x32_bf16 v[96:99], v[196:199], v[212:215], v[96:99]
	v_mfma_f32_16x16x32_bf16 v[84:87], v[188:191], v[220:223], v[84:87]
	v_mfma_f32_16x16x32_bf16 v[80:83], v[196:199], v[220:223], v[80:83]
	s_setprio 3
	s_barrier
	v_mfma_f32_16x16x32_bf16 v[68:71], v[188:191], v[228:231], v[68:71]
	v_mfma_f32_16x16x32_bf16 v[64:67], v[196:199], v[228:231], v[64:67]
	s_setprio 0
	s_add_i32 s34, s57, s37
	v_lshl_add_u64 v[160:161], v[160:161], 0, s[14:15]
	s_mov_b32 m0, s34
	ds_read_b128 v[200:203], v175 offset:49152
	ds_read_b128 v[204:207], v175 offset:50176
	ds_read_b128 v[208:211], v175 offset:51200
	ds_read_b128 v[212:215], v175 offset:52224
	ds_read_b128 v[216:219], v175 offset:53248
	ds_read_b128 v[220:223], v175 offset:54272
	ds_read_b128 v[224:227], v175 offset:55296
	ds_read_b128 v[228:231], v175 offset:56320
	global_load_lds_dwordx4 v[160:161], off
	s_add_i32 m0, s34, 0x2000
	s_add_u32 s30, s30, 0x40080
	v_lshl_add_u64 v[160:161], v[178:179], 0, s[14:15]
	s_addc_u32 s31, s31, 0
	s_add_i32 s34, s58, s37
	global_load_lds_dwordx4 v[160:161], off
	v_lshl_add_u64 v[160:161], s[30:31], 0, v[130:131]
	s_mov_b32 m0, s34
	s_nop 0
	global_load_lds_dwordx4 v[160:161], off
	v_lshl_add_u64 v[160:161], s[30:31], 0, v[134:135]
	s_add_i32 m0, s34, 0x2000
	s_nop 0
	global_load_lds_dwordx4 v[160:161], off
	s_waitcnt vmcnt(6)
	s_waitcnt lgkmcnt(0)
	s_barrier
	s_waitcnt lgkmcnt(0)
	v_mfma_f32_16x16x32_bf16 v[60:63], v[144:147], v[200:203], v[60:63]
	v_mfma_f32_16x16x32_bf16 v[56:59], v[152:155], v[200:203], v[56:59]
	v_mfma_f32_16x16x32_bf16 v[44:47], v[144:147], v[208:211], v[44:47]
	v_mfma_f32_16x16x32_bf16 v[40:43], v[152:155], v[208:211], v[40:43]
	v_mfma_f32_16x16x32_bf16 v[28:31], v[144:147], v[216:219], v[28:31]
	v_mfma_f32_16x16x32_bf16 v[24:27], v[152:155], v[216:219], v[24:27]
	v_mfma_f32_16x16x32_bf16 v[12:15], v[144:147], v[224:227], v[12:15]
	v_mfma_f32_16x16x32_bf16 v[8:11], v[152:155], v[224:227], v[8:11]
	v_mfma_f32_16x16x32_bf16 v[60:63], v[148:151], v[204:207], v[60:63]
	v_mfma_f32_16x16x32_bf16 v[56:59], v[156:159], v[204:207], v[56:59]
	v_mfma_f32_16x16x32_bf16 v[44:47], v[148:151], v[212:215], v[44:47]
	v_mfma_f32_16x16x32_bf16 v[40:43], v[156:159], v[212:215], v[40:43]
	v_mfma_f32_16x16x32_bf16 v[28:31], v[148:151], v[220:223], v[28:31]
	v_mfma_f32_16x16x32_bf16 v[24:27], v[156:159], v[220:223], v[24:27]
	v_mfma_f32_16x16x32_bf16 v[12:15], v[148:151], v[228:231], v[12:15]
	v_mfma_f32_16x16x32_bf16 v[8:11], v[156:159], v[228:231], v[8:11]
	v_mfma_f32_16x16x32_bf16 v[52:55], v[184:187], v[200:203], v[52:55]
	v_mfma_f32_16x16x32_bf16 v[48:51], v[192:195], v[200:203], v[48:51]
	v_mfma_f32_16x16x32_bf16 v[36:39], v[184:187], v[208:211], v[36:39]
	v_mfma_f32_16x16x32_bf16 v[32:35], v[192:195], v[208:211], v[32:35]
	v_mfma_f32_16x16x32_bf16 v[20:23], v[184:187], v[216:219], v[20:23]
	v_mfma_f32_16x16x32_bf16 v[16:19], v[192:195], v[216:219], v[16:19]
	v_mfma_f32_16x16x32_bf16 v[4:7], v[184:187], v[224:227], v[4:7]
	v_mfma_f32_16x16x32_bf16 v[0:3], v[192:195], v[224:227], v[0:3]
	v_mfma_f32_16x16x32_bf16 v[52:55], v[188:191], v[204:207], v[52:55]
	v_mfma_f32_16x16x32_bf16 v[48:51], v[196:199], v[204:207], v[48:51]
	v_mfma_f32_16x16x32_bf16 v[36:39], v[188:191], v[212:215], v[36:39]
	v_mfma_f32_16x16x32_bf16 v[32:35], v[196:199], v[212:215], v[32:35]
	v_mfma_f32_16x16x32_bf16 v[20:23], v[188:191], v[220:223], v[20:23]
	v_mfma_f32_16x16x32_bf16 v[16:19], v[196:199], v[220:223], v[16:19]
	s_setprio 3
	s_barrier
	v_mfma_f32_16x16x32_bf16 v[4:7], v[188:191], v[228:231], v[4:7]
	v_mfma_f32_16x16x32_bf16 v[0:3], v[196:199], v[228:231], v[0:3]
	s_setprio 0
	v_lshl_add_u64 v[160:161], v[232:233], 0, s[14:15]
	s_mov_b32 m0, s42
	s_nop 0
	global_load_lds_dwordx4 v[160:161], off
	v_lshl_add_u64 v[160:161], v[234:235], 0, s[14:15]
	s_mov_b32 m0, s43
	s_nop 0
	global_load_lds_dwordx4 v[160:161], off
	s_add_i32 s56, s56, 2
	s_add_u32 s28, s28, 0x100
	s_addc_u32 s29, s29, 0
	s_add_u32 s54, s54, 0x100
	s_addc_u32 s55, s55, 0
	s_cmp_gt_u32 s56, 13

.LBB0_1290:
	s_ashr_i32 s17, s16, 31
	s_lshl_b64 s[18:19], s[16:17], 19
	s_add_u32 s18, s48, s18
	s_addc_u32 s19, s49, s19
	s_and_b64 s[20:21], s[4:5], exec
	s_cselect_b32 s17, s19, s25
	s_cselect_b32 s23, s18, s24
	s_ashr_i32 s15, s14, 31
	s_lshl_b64 s[20:21], s[14:15], 19
	s_add_u32 s20, s30, s20
	s_addc_u32 s21, s31, s21
	s_and_b64 s[28:29], s[4:5], exec
	s_cselect_b32 s15, s21, s27
	s_cselect_b32 s44, s20, s26
	s_add_u32 s24, s24, 0x40080
	s_addc_u32 s25, s25, 0
	s_add_u32 s45, s26, 0x100
	s_addc_u32 s46, s27, 0
	s_mov_b32 s47, -2
	s_waitcnt lgkmcnt(0)
	ds_read_b128 v[144:147], v151
	ds_read_b128 v[156:159], v151 offset:1024
	ds_read_b128 v[160:163], v151 offset:2048
	ds_read_b128 v[164:167], v151 offset:3072
	ds_read_b128 v[168:171], v152
	ds_read_b128 v[172:175], v152 offset:1024
	ds_read_b128 v[176:179], v152 offset:2048
	ds_read_b128 v[184:187], v152 offset:3072
	s_add_u32 s26, s24, 0xfffc0080
	s_addc_u32 s27, s25, -1
	s_cmp_eq_u32 s47, 12
	s_cselect_b32 s29, s17, s27
	s_cselect_b32 s28, s23, s26
	s_cselect_b32 s27, s15, s46
	s_cselect_b32 s26, s44, s45
	v_lshl_add_u64 v[220:221], s[24:25], 0, v[136:137]
	s_add_i32 m0, s34, 0xc000
	ds_read_b128 v[188:191], v153
	ds_read_b128 v[192:195], v153 offset:1024
	ds_read_b128 v[196:199], v153 offset:2048
	ds_read_b128 v[200:203], v153 offset:3072
	ds_read_b128 v[204:207], v153 offset:4096
	ds_read_b128 v[208:211], v153 offset:5120
	ds_read_b128 v[212:215], v153 offset:6144
	ds_read_b128 v[216:219], v153 offset:7168
	global_load_lds_dwordx4 v[220:221], off
	v_lshl_add_u64 v[220:221], s[24:25], 0, v[138:139]
	s_add_i32 m0, s34, 0xe000
	s_nop 0
	global_load_lds_dwordx4 v[220:221], off
	s_waitcnt vmcnt(8)
	s_waitcnt lgkmcnt(0)
	s_barrier
	s_waitcnt lgkmcnt(0)
	v_mfma_f32_16x16x32_bf16 v[124:127], v[144:147], v[188:191], 0
	v_mfma_f32_16x16x32_bf16 v[120:123], v[160:163], v[188:191], 0
	v_mfma_f32_16x16x32_bf16 v[108:111], v[144:147], v[196:199], 0
	v_mfma_f32_16x16x32_bf16 v[104:107], v[160:163], v[196:199], 0
	v_mfma_f32_16x16x32_bf16 v[92:95], v[144:147], v[204:207], 0
	v_mfma_f32_16x16x32_bf16 v[88:91], v[160:163], v[204:207], 0
	v_mfma_f32_16x16x32_bf16 v[76:79], v[144:147], v[212:215], 0
	v_mfma_f32_16x16x32_bf16 v[72:75], v[160:163], v[212:215], 0
	v_mfma_f32_16x16x32_bf16 v[124:127], v[156:159], v[192:195], v[124:127]
	v_mfma_f32_16x16x32_bf16 v[120:123], v[164:167], v[192:195], v[120:123]
	v_mfma_f32_16x16x32_bf16 v[108:111], v[156:159], v[200:203], v[108:111]
	v_mfma_f32_16x16x32_bf16 v[104:107], v[164:167], v[200:203], v[104:107]
	v_mfma_f32_16x16x32_bf16 v[92:95], v[156:159], v[208:211], v[92:95]
	v_mfma_f32_16x16x32_bf16 v[88:91], v[164:167], v[208:211], v[88:91]
	v_mfma_f32_16x16x32_bf16 v[76:79], v[156:159], v[216:219], v[76:79]
	v_mfma_f32_16x16x32_bf16 v[72:75], v[164:167], v[216:219], v[72:75]
	v_mfma_f32_16x16x32_bf16 v[116:119], v[168:171], v[188:191], 0
	v_mfma_f32_16x16x32_bf16 v[112:115], v[176:179], v[188:191], 0
	v_mfma_f32_16x16x32_bf16 v[100:103], v[168:171], v[196:199], 0
	v_mfma_f32_16x16x32_bf16 v[96:99], v[176:179], v[196:199], 0
	v_mfma_f32_16x16x32_bf16 v[84:87], v[168:171], v[204:207], 0
	v_mfma_f32_16x16x32_bf16 v[80:83], v[176:179], v[204:207], 0
	v_mfma_f32_16x16x32_bf16 v[68:71], v[168:171], v[212:215], 0
	v_mfma_f32_16x16x32_bf16 v[64:67], v[176:179], v[212:215], 0
	v_mfma_f32_16x16x32_bf16 v[116:119], v[172:175], v[192:195], v[116:119]
	v_mfma_f32_16x16x32_bf16 v[112:115], v[184:187], v[192:195], v[112:115]
	v_mfma_f32_16x16x32_bf16 v[100:103], v[172:175], v[200:203], v[100:103]
	v_mfma_f32_16x16x32_bf16 v[96:99], v[184:187], v[200:203], v[96:99]
	v_mfma_f32_16x16x32_bf16 v[84:87], v[172:175], v[208:211], v[84:87]
	v_mfma_f32_16x16x32_bf16 v[80:83], v[184:187], v[208:211], v[80:83]
	s_setprio 3
	s_barrier
	v_mfma_f32_16x16x32_bf16 v[68:71], v[172:175], v[216:219], v[68:71]
	v_mfma_f32_16x16x32_bf16 v[64:67], v[184:187], v[216:219], v[64:67]
	s_setprio 0
	s_add_i32 s50, s41, s33
	v_lshl_add_u64 v[220:221], s[26:27], 0, v[130:131]
	s_mov_b32 m0, s50
	ds_read_b128 v[188:191], v153 offset:16384
	ds_read_b128 v[192:195], v153 offset:17408
	ds_read_b128 v[196:199], v153 offset:18432
	ds_read_b128 v[200:203], v153 offset:19456
	ds_read_b128 v[204:207], v153 offset:20480
	ds_read_b128 v[208:211], v153 offset:21504
	ds_read_b128 v[212:215], v153 offset:22528
	ds_read_b128 v[216:219], v153 offset:23552
	global_load_lds_dwordx4 v[220:221], off
	s_add_i32 m0, s50, 0x2000
	s_add_u32 s50, s26, 0x40000
	v_lshl_add_u64 v[222:223], s[26:27], 0, v[134:135]
	s_addc_u32 s51, s27, 0
	s_add_i32 s52, s42, s33
	global_load_lds_dwordx4 v[222:223], off
	v_lshl_add_u64 v[224:225], s[50:51], 0, v[130:131]
	s_mov_b32 m0, s52
	global_load_lds_dwordx4 v[224:225], off
	v_lshl_add_u64 v[224:225], s[50:51], 0, v[134:135]
	s_add_i32 m0, s52, 0x2000
	s_nop 0
	global_load_lds_dwordx4 v[224:225], off
	s_waitcnt vmcnt(6)
	s_waitcnt lgkmcnt(0)
	s_barrier
	s_waitcnt lgkmcnt(0)
	v_mfma_f32_16x16x32_bf16 v[60:63], v[144:147], v[188:191], 0
	v_mfma_f32_16x16x32_bf16 v[56:59], v[160:163], v[188:191], 0
	v_mfma_f32_16x16x32_bf16 v[44:47], v[144:147], v[196:199], 0
	v_mfma_f32_16x16x32_bf16 v[40:43], v[160:163], v[196:199], 0
	v_mfma_f32_16x16x32_bf16 v[28:31], v[144:147], v[204:207], 0
	v_mfma_f32_16x16x32_bf16 v[24:27], v[160:163], v[204:207], 0
	v_mfma_f32_16x16x32_bf16 v[12:15], v[144:147], v[212:215], 0
	v_mfma_f32_16x16x32_bf16 v[8:11], v[160:163], v[212:215], 0
	v_mfma_f32_16x16x32_bf16 v[60:63], v[156:159], v[192:195], v[60:63]
	v_mfma_f32_16x16x32_bf16 v[56:59], v[164:167], v[192:195], v[56:59]
	v_mfma_f32_16x16x32_bf16 v[44:47], v[156:159], v[200:203], v[44:47]
	v_mfma_f32_16x16x32_bf16 v[40:43], v[164:167], v[200:203], v[40:43]
	v_mfma_f32_16x16x32_bf16 v[28:31], v[156:159], v[208:211], v[28:31]
	v_mfma_f32_16x16x32_bf16 v[24:27], v[164:167], v[208:211], v[24:27]
	v_mfma_f32_16x16x32_bf16 v[12:15], v[156:159], v[216:219], v[12:15]
	v_mfma_f32_16x16x32_bf16 v[8:11], v[164:167], v[216:219], v[8:11]
	v_mfma_f32_16x16x32_bf16 v[52:55], v[168:171], v[188:191], 0
	v_mfma_f32_16x16x32_bf16 v[48:51], v[176:179], v[188:191], 0
	v_mfma_f32_16x16x32_bf16 v[36:39], v[168:171], v[196:199], 0
	v_mfma_f32_16x16x32_bf16 v[32:35], v[176:179], v[196:199], 0
	v_mfma_f32_16x16x32_bf16 v[20:23], v[168:171], v[204:207], 0
	v_mfma_f32_16x16x32_bf16 v[16:19], v[176:179], v[204:207], 0
	v_mfma_f32_16x16x32_bf16 v[4:7], v[168:171], v[212:215], 0
	v_mfma_f32_16x16x32_bf16 v[0:3], v[176:179], v[212:215], 0
	v_mfma_f32_16x16x32_bf16 v[52:55], v[172:175], v[192:195], v[52:55]
	v_mfma_f32_16x16x32_bf16 v[48:51], v[184:187], v[192:195], v[48:51]
	v_mfma_f32_16x16x32_bf16 v[36:39], v[172:175], v[200:203], v[36:39]
	v_mfma_f32_16x16x32_bf16 v[32:35], v[184:187], v[200:203], v[32:35]
	v_mfma_f32_16x16x32_bf16 v[20:23], v[172:175], v[208:211], v[20:23]
	v_mfma_f32_16x16x32_bf16 v[16:19], v[184:187], v[208:211], v[16:19]
	s_setprio 3
	s_barrier
	v_mfma_f32_16x16x32_bf16 v[4:7], v[172:175], v[216:219], v[4:7]
	v_mfma_f32_16x16x32_bf16 v[0:3], v[184:187], v[216:219], v[0:3]
	s_setprio 0
	s_add_i32 s50, 0, 0x18000
	v_add_u32_e32 v155, s50, v149
	s_add_i32 s51, 0, 0x1c000
	ds_read_b128 v[144:147], v155
	ds_read_b128 v[156:159], v155 offset:1024
	ds_read_b128 v[160:163], v155 offset:2048
	ds_read_b128 v[164:167], v155 offset:3072
	v_add_u32_e32 v155, s51, v149
	ds_read_b128 v[168:171], v155
	ds_read_b128 v[172:175], v155 offset:1024
	ds_read_b128 v[176:179], v155 offset:2048
	ds_read_b128 v[184:187], v155 offset:3072
	v_lshl_add_u64 v[224:225], s[28:29], 0, v[128:129]
	s_mov_b32 m0, s34
	v_lshl_add_u64 v[226:227], s[28:29], 0, v[132:133]
	global_load_lds_dwordx4 v[224:225], off
	s_mov_b32 m0, s35
	s_nop 0
	global_load_lds_dwordx4 v[226:227], off
	s_add_u32 s28, s28, 0x40000
	s_addc_u32 s29, s29, 0
	s_mov_b32 m0, s36
	v_lshl_add_u64 v[228:229], s[28:29], 0, v[128:129]
	ds_read_b128 v[188:191], v153 offset:32768
	ds_read_b128 v[192:195], v153 offset:33792
	ds_read_b128 v[196:199], v153 offset:34816
	ds_read_b128 v[200:203], v153 offset:35840
	ds_read_b128 v[204:207], v153 offset:36864
	ds_read_b128 v[208:211], v153 offset:37888
	ds_read_b128 v[212:215], v153 offset:38912
	ds_read_b128 v[216:219], v153 offset:39936
	global_load_lds_dwordx4 v[228:229], off
	v_lshl_add_u64 v[228:229], s[28:29], 0, v[132:133]
	s_mov_b32 m0, s37
	s_nop 0
	global_load_lds_dwordx4 v[228:229], off
	s_waitcnt vmcnt(8)
	s_waitcnt lgkmcnt(0)
	s_barrier
	s_waitcnt lgkmcnt(0)
	v_mfma_f32_16x16x32_bf16 v[124:127], v[144:147], v[188:191], v[124:127]
	v_mfma_f32_16x16x32_bf16 v[120:123], v[160:163], v[188:191], v[120:123]
	v_mfma_f32_16x16x32_bf16 v[108:111], v[144:147], v[196:199], v[108:111]
	v_mfma_f32_16x16x32_bf16 v[104:107], v[160:163], v[196:199], v[104:107]
	v_mfma_f32_16x16x32_bf16 v[92:95], v[144:147], v[204:207], v[92:95]
	v_mfma_f32_16x16x32_bf16 v[88:91], v[160:163], v[204:207], v[88:91]
	v_mfma_f32_16x16x32_bf16 v[76:79], v[144:147], v[212:215], v[76:79]
	v_mfma_f32_16x16x32_bf16 v[72:75], v[160:163], v[212:215], v[72:75]
	v_mfma_f32_16x16x32_bf16 v[124:127], v[156:159], v[192:195], v[124:127]
	v_mfma_f32_16x16x32_bf16 v[120:123], v[164:167], v[192:195], v[120:123]
	v_mfma_f32_16x16x32_bf16 v[108:111], v[156:159], v[200:203], v[108:111]
	v_mfma_f32_16x16x32_bf16 v[104:107], v[164:167], v[200:203], v[104:107]
	v_mfma_f32_16x16x32_bf16 v[92:95], v[156:159], v[208:211], v[92:95]
	v_mfma_f32_16x16x32_bf16 v[88:91], v[164:167], v[208:211], v[88:91]
	v_mfma_f32_16x16x32_bf16 v[76:79], v[156:159], v[216:219], v[76:79]
	v_mfma_f32_16x16x32_bf16 v[72:75], v[164:167], v[216:219], v[72:75]
	v_mfma_f32_16x16x32_bf16 v[116:119], v[168:171], v[188:191], v[116:119]
	v_mfma_f32_16x16x32_bf16 v[112:115], v[176:179], v[188:191], v[112:115]
	v_mfma_f32_16x16x32_bf16 v[100:103], v[168:171], v[196:199], v[100:103]
	v_mfma_f32_16x16x32_bf16 v[96:99], v[176:179], v[196:199], v[96:99]
	v_mfma_f32_16x16x32_bf16 v[84:87], v[168:171], v[204:207], v[84:87]
	v_mfma_f32_16x16x32_bf16 v[80:83], v[176:179], v[204:207], v[80:83]
	v_mfma_f32_16x16x32_bf16 v[68:71], v[168:171], v[212:215], v[68:71]
	v_mfma_f32_16x16x32_bf16 v[64:67], v[176:179], v[212:215], v[64:67]
	v_mfma_f32_16x16x32_bf16 v[116:119], v[172:175], v[192:195], v[116:119]
	v_mfma_f32_16x16x32_bf16 v[112:115], v[184:187], v[192:195], v[112:115]
	v_mfma_f32_16x16x32_bf16 v[100:103], v[172:175], v[200:203], v[100:103]
	v_mfma_f32_16x16x32_bf16 v[96:99], v[184:187], v[200:203], v[96:99]
	v_mfma_f32_16x16x32_bf16 v[84:87], v[172:175], v[208:211], v[84:87]
	v_mfma_f32_16x16x32_bf16 v[80:83], v[184:187], v[208:211], v[80:83]
	s_setprio 3
	s_barrier
	v_mfma_f32_16x16x32_bf16 v[68:71], v[172:175], v[216:219], v[68:71]
	v_mfma_f32_16x16x32_bf16 v[64:67], v[184:187], v[216:219], v[64:67]
	s_setprio 0
	s_add_i32 s28, s50, s33
	v_lshl_add_u64 v[220:221], v[220:221], 0, s[10:11]
	s_mov_b32 m0, s28
	ds_read_b128 v[188:191], v153 offset:49152
	ds_read_b128 v[192:195], v153 offset:50176
	ds_read_b128 v[196:199], v153 offset:51200
	ds_read_b128 v[200:203], v153 offset:52224
	ds_read_b128 v[204:207], v153 offset:53248
	ds_read_b128 v[208:211], v153 offset:54272
	ds_read_b128 v[212:215], v153 offset:55296
	ds_read_b128 v[216:219], v153 offset:56320
	global_load_lds_dwordx4 v[220:221], off
	s_add_i32 m0, s28, 0x2000
	s_add_u32 s26, s26, 0x40080
	v_lshl_add_u64 v[220:221], v[222:223], 0, s[10:11]
	s_addc_u32 s27, s27, 0
	s_add_i32 s28, s51, s33
	global_load_lds_dwordx4 v[220:221], off
	v_lshl_add_u64 v[220:221], s[26:27], 0, v[130:131]
	s_mov_b32 m0, s28
	s_nop 0
	global_load_lds_dwordx4 v[220:221], off
	v_lshl_add_u64 v[220:221], s[26:27], 0, v[134:135]
	s_add_i32 m0, s28, 0x2000
	s_nop 0
	global_load_lds_dwordx4 v[220:221], off
	s_waitcnt vmcnt(6)
	s_waitcnt lgkmcnt(0)
	s_barrier
	s_waitcnt lgkmcnt(0)
	v_mfma_f32_16x16x32_bf16 v[60:63], v[144:147], v[188:191], v[60:63]
	v_mfma_f32_16x16x32_bf16 v[56:59], v[160:163], v[188:191], v[56:59]
	v_mfma_f32_16x16x32_bf16 v[44:47], v[144:147], v[196:199], v[44:47]
	v_mfma_f32_16x16x32_bf16 v[40:43], v[160:163], v[196:199], v[40:43]
	v_mfma_f32_16x16x32_bf16 v[28:31], v[144:147], v[204:207], v[28:31]
	v_mfma_f32_16x16x32_bf16 v[24:27], v[160:163], v[204:207], v[24:27]
	v_mfma_f32_16x16x32_bf16 v[12:15], v[144:147], v[212:215], v[12:15]
	v_mfma_f32_16x16x32_bf16 v[8:11], v[160:163], v[212:215], v[8:11]
	v_mfma_f32_16x16x32_bf16 v[60:63], v[156:159], v[192:195], v[60:63]
	v_mfma_f32_16x16x32_bf16 v[56:59], v[164:167], v[192:195], v[56:59]
	v_mfma_f32_16x16x32_bf16 v[44:47], v[156:159], v[200:203], v[44:47]
	v_mfma_f32_16x16x32_bf16 v[40:43], v[164:167], v[200:203], v[40:43]
	v_mfma_f32_16x16x32_bf16 v[28:31], v[156:159], v[208:211], v[28:31]
	v_mfma_f32_16x16x32_bf16 v[24:27], v[164:167], v[208:211], v[24:27]
	v_mfma_f32_16x16x32_bf16 v[12:15], v[156:159], v[216:219], v[12:15]
	v_mfma_f32_16x16x32_bf16 v[8:11], v[164:167], v[216:219], v[8:11]
	v_mfma_f32_16x16x32_bf16 v[52:55], v[168:171], v[188:191], v[52:55]
	v_mfma_f32_16x16x32_bf16 v[48:51], v[176:179], v[188:191], v[48:51]
	v_mfma_f32_16x16x32_bf16 v[36:39], v[168:171], v[196:199], v[36:39]
	v_mfma_f32_16x16x32_bf16 v[32:35], v[176:179], v[196:199], v[32:35]
	v_mfma_f32_16x16x32_bf16 v[20:23], v[168:171], v[204:207], v[20:23]
	v_mfma_f32_16x16x32_bf16 v[16:19], v[176:179], v[204:207], v[16:19]
	v_mfma_f32_16x16x32_bf16 v[4:7], v[168:171], v[212:215], v[4:7]
	v_mfma_f32_16x16x32_bf16 v[0:3], v[176:179], v[212:215], v[0:3]
	v_mfma_f32_16x16x32_bf16 v[52:55], v[172:175], v[192:195], v[52:55]
	v_mfma_f32_16x16x32_bf16 v[48:51], v[184:187], v[192:195], v[48:51]
	v_mfma_f32_16x16x32_bf16 v[36:39], v[172:175], v[200:203], v[36:39]
	v_mfma_f32_16x16x32_bf16 v[32:35], v[184:187], v[200:203], v[32:35]
	v_mfma_f32_16x16x32_bf16 v[20:23], v[172:175], v[208:211], v[20:23]
	v_mfma_f32_16x16x32_bf16 v[16:19], v[184:187], v[208:211], v[16:19]
	s_setprio 3
	s_barrier
	v_mfma_f32_16x16x32_bf16 v[4:7], v[172:175], v[216:219], v[4:7]
	v_mfma_f32_16x16x32_bf16 v[0:3], v[184:187], v[216:219], v[0:3]
	s_setprio 0
	v_lshl_add_u64 v[220:221], v[224:225], 0, s[10:11]
	s_mov_b32 m0, s39
	s_nop 0
	global_load_lds_dwordx4 v[220:221], off
	v_lshl_add_u64 v[220:221], v[226:227], 0, s[10:11]
	s_mov_b32 m0, s40
	s_nop 0
	global_load_lds_dwordx4 v[220:221], off
	s_add_i32 s47, s47, 2
	s_add_u32 s24, s24, 0x100
	s_addc_u32 s25, s25, 0
	s_add_u32 s45, s45, 0x100
	s_addc_u32 s46, s46, 0
	s_cmp_gt_u32 s47, 13

.LBB0_1378:
	s_ashr_i32 s13, s12, 31
	s_lshl_b64 s[14:15], s[12:13], 19
	s_add_u32 s14, s74, s14
	s_addc_u32 s15, s75, s15
	s_and_b64 s[16:17], s[0:1], exec
	s_cselect_b32 s13, s15, s21
	s_cselect_b32 s42, s14, s20
	s_ashr_i32 s11, s10, 31
	s_lshl_b64 s[16:17], s[10:11], 19
	s_add_u32 s16, s26, s16
	s_addc_u32 s17, s27, s17
	s_and_b64 s[24:25], s[0:1], exec
	s_cselect_b32 s11, s17, s23
	s_cselect_b32 s43, s16, s22
	s_add_u32 s20, s20, 0x40080
	s_addc_u32 s21, s21, 0
	s_add_u32 s44, s22, 0x100
	s_addc_u32 s45, s23, 0
	s_mov_b32 s46, -2
	ds_read_b128 v[154:157], v151
	ds_read_b128 v[158:161], v151 offset:1024
	ds_read_b128 v[162:165], v151 offset:2048
	ds_read_b128 v[166:169], v151 offset:3072
	ds_read_b128 v[170:173], v152
	ds_read_b128 v[174:177], v152 offset:1024
	ds_read_b128 v[184:187], v152 offset:2048
	ds_read_b128 v[188:191], v152 offset:3072
	s_add_u32 s22, s20, 0xfffc0080
	s_addc_u32 s23, s21, -1
	s_cmp_eq_u32 s46, 12
	s_cselect_b32 s25, s13, s23
	s_cselect_b32 s24, s42, s22
	s_cselect_b32 s23, s11, s45
	s_cselect_b32 s22, s43, s44
	v_lshl_add_u64 v[178:179], s[20:21], 0, v[136:137]
	s_add_i32 m0, s19, 0xc000
	ds_read_b128 v[192:195], v153
	ds_read_b128 v[196:199], v153 offset:1024
	ds_read_b128 v[200:203], v153 offset:2048
	ds_read_b128 v[204:207], v153 offset:3072
	ds_read_b128 v[208:211], v153 offset:4096
	ds_read_b128 v[212:215], v153 offset:5120
	ds_read_b128 v[216:219], v153 offset:6144
	ds_read_b128 v[220:223], v153 offset:7168
	global_load_lds_dwordx4 v[178:179], off
	v_lshl_add_u64 v[178:179], s[20:21], 0, v[138:139]
	s_add_i32 m0, s19, 0xe000
	s_nop 0
	global_load_lds_dwordx4 v[178:179], off
	s_waitcnt vmcnt(8)
	s_waitcnt lgkmcnt(0)
	s_barrier
	s_waitcnt lgkmcnt(0)
	v_mfma_f32_16x16x32_bf16 v[124:127], v[154:157], v[192:195], 0
	v_mfma_f32_16x16x32_bf16 v[116:119], v[162:165], v[192:195], 0
	v_mfma_f32_16x16x32_bf16 v[108:111], v[154:157], v[200:203], 0
	v_mfma_f32_16x16x32_bf16 v[100:103], v[162:165], v[200:203], 0
	v_mfma_f32_16x16x32_bf16 v[92:95], v[154:157], v[208:211], 0
	v_mfma_f32_16x16x32_bf16 v[84:87], v[162:165], v[208:211], 0
	v_mfma_f32_16x16x32_bf16 v[76:79], v[154:157], v[216:219], 0
	v_mfma_f32_16x16x32_bf16 v[68:71], v[162:165], v[216:219], 0
	v_mfma_f32_16x16x32_bf16 v[124:127], v[158:161], v[196:199], v[124:127]
	v_mfma_f32_16x16x32_bf16 v[116:119], v[166:169], v[196:199], v[116:119]
	v_mfma_f32_16x16x32_bf16 v[108:111], v[158:161], v[204:207], v[108:111]
	v_mfma_f32_16x16x32_bf16 v[100:103], v[166:169], v[204:207], v[100:103]
	v_mfma_f32_16x16x32_bf16 v[92:95], v[158:161], v[212:215], v[92:95]
	v_mfma_f32_16x16x32_bf16 v[84:87], v[166:169], v[212:215], v[84:87]
	v_mfma_f32_16x16x32_bf16 v[76:79], v[158:161], v[220:223], v[76:79]
	v_mfma_f32_16x16x32_bf16 v[68:71], v[166:169], v[220:223], v[68:71]
	v_mfma_f32_16x16x32_bf16 v[120:123], v[170:173], v[192:195], 0
	v_mfma_f32_16x16x32_bf16 v[112:115], v[184:187], v[192:195], 0
	v_mfma_f32_16x16x32_bf16 v[104:107], v[170:173], v[200:203], 0
	v_mfma_f32_16x16x32_bf16 v[96:99], v[184:187], v[200:203], 0
	v_mfma_f32_16x16x32_bf16 v[88:91], v[170:173], v[208:211], 0
	v_mfma_f32_16x16x32_bf16 v[80:83], v[184:187], v[208:211], 0
	v_mfma_f32_16x16x32_bf16 v[72:75], v[170:173], v[216:219], 0
	v_mfma_f32_16x16x32_bf16 v[64:67], v[184:187], v[216:219], 0
	v_mfma_f32_16x16x32_bf16 v[120:123], v[174:177], v[196:199], v[120:123]
	v_mfma_f32_16x16x32_bf16 v[112:115], v[188:191], v[196:199], v[112:115]
	v_mfma_f32_16x16x32_bf16 v[104:107], v[174:177], v[204:207], v[104:107]
	v_mfma_f32_16x16x32_bf16 v[96:99], v[188:191], v[204:207], v[96:99]
	v_mfma_f32_16x16x32_bf16 v[88:91], v[174:177], v[212:215], v[88:91]
	v_mfma_f32_16x16x32_bf16 v[80:83], v[188:191], v[212:215], v[80:83]
	s_setprio 3
	s_barrier
	v_mfma_f32_16x16x32_bf16 v[72:75], v[174:177], v[220:223], v[72:75]
	v_mfma_f32_16x16x32_bf16 v[64:67], v[188:191], v[220:223], v[64:67]
	s_setprio 0
	s_add_i32 s47, s36, s28
	v_lshl_add_u64 v[178:179], s[22:23], 0, v[132:133]
	s_mov_b32 m0, s47
	ds_read_b128 v[192:195], v153 offset:16384
	ds_read_b128 v[196:199], v153 offset:17408
	ds_read_b128 v[200:203], v153 offset:18432
	ds_read_b128 v[204:207], v153 offset:19456
	ds_read_b128 v[208:211], v153 offset:20480
	ds_read_b128 v[212:215], v153 offset:21504
	ds_read_b128 v[216:219], v153 offset:22528
	ds_read_b128 v[220:223], v153 offset:23552
	global_load_lds_dwordx4 v[178:179], off
	s_add_i32 m0, s47, 0x2000
	s_add_u32 s48, s22, 0x40000
	v_lshl_add_u64 v[224:225], s[22:23], 0, v[128:129]
	s_addc_u32 s49, s23, 0
	s_add_i32 s47, s37, s28
	global_load_lds_dwordx4 v[224:225], off
	v_lshl_add_u64 v[226:227], s[48:49], 0, v[132:133]
	s_mov_b32 m0, s47
	global_load_lds_dwordx4 v[226:227], off
	v_lshl_add_u64 v[226:227], s[48:49], 0, v[128:129]
	s_add_i32 m0, s47, 0x2000
	s_nop 0
	global_load_lds_dwordx4 v[226:227], off
	s_waitcnt vmcnt(6)
	s_waitcnt lgkmcnt(0)
	s_barrier
	s_waitcnt lgkmcnt(0)
	v_mfma_f32_16x16x32_bf16 v[60:63], v[154:157], v[192:195], 0
	v_mfma_f32_16x16x32_bf16 v[52:55], v[162:165], v[192:195], 0
	v_mfma_f32_16x16x32_bf16 v[44:47], v[154:157], v[200:203], 0
	v_mfma_f32_16x16x32_bf16 v[36:39], v[162:165], v[200:203], 0
	v_mfma_f32_16x16x32_bf16 v[28:31], v[154:157], v[208:211], 0
	v_mfma_f32_16x16x32_bf16 v[20:23], v[162:165], v[208:211], 0
	v_mfma_f32_16x16x32_bf16 v[12:15], v[154:157], v[216:219], 0
	v_mfma_f32_16x16x32_bf16 v[4:7], v[162:165], v[216:219], 0
	v_mfma_f32_16x16x32_bf16 v[60:63], v[158:161], v[196:199], v[60:63]
	v_mfma_f32_16x16x32_bf16 v[52:55], v[166:169], v[196:199], v[52:55]
	v_mfma_f32_16x16x32_bf16 v[44:47], v[158:161], v[204:207], v[44:47]
	v_mfma_f32_16x16x32_bf16 v[36:39], v[166:169], v[204:207], v[36:39]
	v_mfma_f32_16x16x32_bf16 v[28:31], v[158:161], v[212:215], v[28:31]
	v_mfma_f32_16x16x32_bf16 v[20:23], v[166:169], v[212:215], v[20:23]
	v_mfma_f32_16x16x32_bf16 v[12:15], v[158:161], v[220:223], v[12:15]
	v_mfma_f32_16x16x32_bf16 v[4:7], v[166:169], v[220:223], v[4:7]
	v_mfma_f32_16x16x32_bf16 v[56:59], v[170:173], v[192:195], 0
	v_mfma_f32_16x16x32_bf16 v[48:51], v[184:187], v[192:195], 0
	v_mfma_f32_16x16x32_bf16 v[40:43], v[170:173], v[200:203], 0
	v_mfma_f32_16x16x32_bf16 v[32:35], v[184:187], v[200:203], 0
	v_mfma_f32_16x16x32_bf16 v[24:27], v[170:173], v[208:211], 0
	v_mfma_f32_16x16x32_bf16 v[16:19], v[184:187], v[208:211], 0
	v_mfma_f32_16x16x32_bf16 v[8:11], v[170:173], v[216:219], 0
	v_mfma_f32_16x16x32_bf16 v[0:3], v[184:187], v[216:219], 0
	v_mfma_f32_16x16x32_bf16 v[56:59], v[174:177], v[196:199], v[56:59]
	v_mfma_f32_16x16x32_bf16 v[48:51], v[188:191], v[196:199], v[48:51]
	v_mfma_f32_16x16x32_bf16 v[40:43], v[174:177], v[204:207], v[40:43]
	v_mfma_f32_16x16x32_bf16 v[32:35], v[188:191], v[204:207], v[32:35]
	v_mfma_f32_16x16x32_bf16 v[24:27], v[174:177], v[212:215], v[24:27]
	v_mfma_f32_16x16x32_bf16 v[16:19], v[188:191], v[212:215], v[16:19]
	s_setprio 3
	s_barrier
	v_mfma_f32_16x16x32_bf16 v[8:11], v[174:177], v[220:223], v[8:11]
	v_mfma_f32_16x16x32_bf16 v[0:3], v[188:191], v[220:223], v[0:3]
	s_setprio 0
	s_add_i32 s47, 0, 0x18000
	s_add_i32 s48, 0, 0x1c000
	v_add_u32_e32 v166, s47, v145
	v_add_u32_e32 v180, s48, v145
	ds_read_b128 v[154:157], v166
	ds_read_b128 v[158:161], v166 offset:1024
	ds_read_b128 v[162:165], v166 offset:2048
	ds_read_b128 v[166:169], v166 offset:3072
	ds_read_b128 v[170:173], v180
	ds_read_b128 v[174:177], v180 offset:1024
	ds_read_b128 v[184:187], v180 offset:2048
	ds_read_b128 v[188:191], v180 offset:3072
	v_lshl_add_u64 v[226:227], s[24:25], 0, v[134:135]
	s_mov_b32 m0, s19
	v_lshl_add_u64 v[228:229], s[24:25], 0, v[130:131]
	global_load_lds_dwordx4 v[226:227], off
	s_mov_b32 m0, s30
	s_nop 0
	global_load_lds_dwordx4 v[228:229], off
	s_add_u32 s24, s24, 0x40000
	s_addc_u32 s25, s25, 0
	s_mov_b32 m0, s31
	v_lshl_add_u64 v[230:231], s[24:25], 0, v[134:135]
	ds_read_b128 v[192:195], v153 offset:32768
	ds_read_b128 v[196:199], v153 offset:33792
	ds_read_b128 v[200:203], v153 offset:34816
	ds_read_b128 v[204:207], v153 offset:35840
	ds_read_b128 v[208:211], v153 offset:36864
	ds_read_b128 v[212:215], v153 offset:37888
	ds_read_b128 v[216:219], v153 offset:38912
	ds_read_b128 v[220:223], v153 offset:39936
	global_load_lds_dwordx4 v[230:231], off
	v_lshl_add_u64 v[230:231], s[24:25], 0, v[130:131]
	s_mov_b32 m0, s33
	s_nop 0
	global_load_lds_dwordx4 v[230:231], off
	s_waitcnt vmcnt(8)
	s_waitcnt lgkmcnt(0)
	s_barrier
	s_waitcnt lgkmcnt(0)
	v_mfma_f32_16x16x32_bf16 v[124:127], v[154:157], v[192:195], v[124:127]
	v_mfma_f32_16x16x32_bf16 v[116:119], v[162:165], v[192:195], v[116:119]
	v_mfma_f32_16x16x32_bf16 v[108:111], v[154:157], v[200:203], v[108:111]
	v_mfma_f32_16x16x32_bf16 v[100:103], v[162:165], v[200:203], v[100:103]
	v_mfma_f32_16x16x32_bf16 v[92:95], v[154:157], v[208:211], v[92:95]
	v_mfma_f32_16x16x32_bf16 v[84:87], v[162:165], v[208:211], v[84:87]
	v_mfma_f32_16x16x32_bf16 v[76:79], v[154:157], v[216:219], v[76:79]
	v_mfma_f32_16x16x32_bf16 v[68:71], v[162:165], v[216:219], v[68:71]
	v_mfma_f32_16x16x32_bf16 v[124:127], v[158:161], v[196:199], v[124:127]
	v_mfma_f32_16x16x32_bf16 v[116:119], v[166:169], v[196:199], v[116:119]
	v_mfma_f32_16x16x32_bf16 v[108:111], v[158:161], v[204:207], v[108:111]
	v_mfma_f32_16x16x32_bf16 v[100:103], v[166:169], v[204:207], v[100:103]
	v_mfma_f32_16x16x32_bf16 v[92:95], v[158:161], v[212:215], v[92:95]
	v_mfma_f32_16x16x32_bf16 v[84:87], v[166:169], v[212:215], v[84:87]
	v_mfma_f32_16x16x32_bf16 v[76:79], v[158:161], v[220:223], v[76:79]
	v_mfma_f32_16x16x32_bf16 v[68:71], v[166:169], v[220:223], v[68:71]
	v_mfma_f32_16x16x32_bf16 v[120:123], v[170:173], v[192:195], v[120:123]
	v_mfma_f32_16x16x32_bf16 v[112:115], v[184:187], v[192:195], v[112:115]
	v_mfma_f32_16x16x32_bf16 v[104:107], v[170:173], v[200:203], v[104:107]
	v_mfma_f32_16x16x32_bf16 v[96:99], v[184:187], v[200:203], v[96:99]
	v_mfma_f32_16x16x32_bf16 v[88:91], v[170:173], v[208:211], v[88:91]
	v_mfma_f32_16x16x32_bf16 v[80:83], v[184:187], v[208:211], v[80:83]
	v_mfma_f32_16x16x32_bf16 v[72:75], v[170:173], v[216:219], v[72:75]
	v_mfma_f32_16x16x32_bf16 v[64:67], v[184:187], v[216:219], v[64:67]
	v_mfma_f32_16x16x32_bf16 v[120:123], v[174:177], v[196:199], v[120:123]
	v_mfma_f32_16x16x32_bf16 v[112:115], v[188:191], v[196:199], v[112:115]
	v_mfma_f32_16x16x32_bf16 v[104:107], v[174:177], v[204:207], v[104:107]
	v_mfma_f32_16x16x32_bf16 v[96:99], v[188:191], v[204:207], v[96:99]
	v_mfma_f32_16x16x32_bf16 v[88:91], v[174:177], v[212:215], v[88:91]
	v_mfma_f32_16x16x32_bf16 v[80:83], v[188:191], v[212:215], v[80:83]
	s_setprio 3
	s_barrier
	v_mfma_f32_16x16x32_bf16 v[72:75], v[174:177], v[220:223], v[72:75]
	v_mfma_f32_16x16x32_bf16 v[64:67], v[188:191], v[220:223], v[64:67]
	s_setprio 0
	s_add_i32 s24, s47, s28
	v_lshl_add_u64 v[178:179], v[178:179], 0, s[6:7]
	s_mov_b32 m0, s24
	ds_read_b128 v[192:195], v153 offset:49152
	ds_read_b128 v[196:199], v153 offset:50176
	ds_read_b128 v[200:203], v153 offset:51200
	ds_read_b128 v[204:207], v153 offset:52224
	ds_read_b128 v[208:211], v153 offset:53248
	ds_read_b128 v[212:215], v153 offset:54272
	ds_read_b128 v[216:219], v153 offset:55296
	ds_read_b128 v[220:223], v153 offset:56320
	global_load_lds_dwordx4 v[178:179], off
	s_add_i32 m0, s24, 0x2000
	s_add_u32 s22, s22, 0x40080
	v_lshl_add_u64 v[178:179], v[224:225], 0, s[6:7]
	s_addc_u32 s23, s23, 0
	s_add_i32 s24, s48, s28
	global_load_lds_dwordx4 v[178:179], off
	v_lshl_add_u64 v[178:179], s[22:23], 0, v[132:133]
	s_mov_b32 m0, s24
	s_nop 0
	global_load_lds_dwordx4 v[178:179], off
	v_lshl_add_u64 v[178:179], s[22:23], 0, v[128:129]
	s_add_i32 m0, s24, 0x2000
	s_nop 0
	global_load_lds_dwordx4 v[178:179], off
	s_waitcnt vmcnt(6)
	s_waitcnt lgkmcnt(0)
	s_barrier
	s_waitcnt lgkmcnt(0)
	v_mfma_f32_16x16x32_bf16 v[60:63], v[154:157], v[192:195], v[60:63]
	v_mfma_f32_16x16x32_bf16 v[52:55], v[162:165], v[192:195], v[52:55]
	v_mfma_f32_16x16x32_bf16 v[44:47], v[154:157], v[200:203], v[44:47]
	v_mfma_f32_16x16x32_bf16 v[36:39], v[162:165], v[200:203], v[36:39]
	v_mfma_f32_16x16x32_bf16 v[28:31], v[154:157], v[208:211], v[28:31]
	v_mfma_f32_16x16x32_bf16 v[20:23], v[162:165], v[208:211], v[20:23]
	v_mfma_f32_16x16x32_bf16 v[12:15], v[154:157], v[216:219], v[12:15]
	v_mfma_f32_16x16x32_bf16 v[4:7], v[162:165], v[216:219], v[4:7]
	v_mfma_f32_16x16x32_bf16 v[60:63], v[158:161], v[196:199], v[60:63]
	v_mfma_f32_16x16x32_bf16 v[52:55], v[166:169], v[196:199], v[52:55]
	v_mfma_f32_16x16x32_bf16 v[44:47], v[158:161], v[204:207], v[44:47]
	v_mfma_f32_16x16x32_bf16 v[36:39], v[166:169], v[204:207], v[36:39]
	v_mfma_f32_16x16x32_bf16 v[28:31], v[158:161], v[212:215], v[28:31]
	v_mfma_f32_16x16x32_bf16 v[20:23], v[166:169], v[212:215], v[20:23]
	v_mfma_f32_16x16x32_bf16 v[12:15], v[158:161], v[220:223], v[12:15]
	v_mfma_f32_16x16x32_bf16 v[4:7], v[166:169], v[220:223], v[4:7]
	v_mfma_f32_16x16x32_bf16 v[56:59], v[170:173], v[192:195], v[56:59]
	v_mfma_f32_16x16x32_bf16 v[48:51], v[184:187], v[192:195], v[48:51]
	v_mfma_f32_16x16x32_bf16 v[40:43], v[170:173], v[200:203], v[40:43]
	v_mfma_f32_16x16x32_bf16 v[32:35], v[184:187], v[200:203], v[32:35]
	v_mfma_f32_16x16x32_bf16 v[24:27], v[170:173], v[208:211], v[24:27]
	v_mfma_f32_16x16x32_bf16 v[16:19], v[184:187], v[208:211], v[16:19]
	v_mfma_f32_16x16x32_bf16 v[8:11], v[170:173], v[216:219], v[8:11]
	v_mfma_f32_16x16x32_bf16 v[0:3], v[184:187], v[216:219], v[0:3]
	v_mfma_f32_16x16x32_bf16 v[56:59], v[174:177], v[196:199], v[56:59]
	v_mfma_f32_16x16x32_bf16 v[48:51], v[188:191], v[196:199], v[48:51]
	v_mfma_f32_16x16x32_bf16 v[40:43], v[174:177], v[204:207], v[40:43]
	v_mfma_f32_16x16x32_bf16 v[32:35], v[188:191], v[204:207], v[32:35]
	v_mfma_f32_16x16x32_bf16 v[24:27], v[174:177], v[212:215], v[24:27]
	v_mfma_f32_16x16x32_bf16 v[16:19], v[188:191], v[212:215], v[16:19]
	s_setprio 3
	s_barrier
	v_mfma_f32_16x16x32_bf16 v[8:11], v[174:177], v[220:223], v[8:11]
	v_mfma_f32_16x16x32_bf16 v[0:3], v[188:191], v[220:223], v[0:3]
	s_setprio 0
	v_lshl_add_u64 v[178:179], v[226:227], 0, s[6:7]
	s_mov_b32 m0, s34
	s_nop 0
	global_load_lds_dwordx4 v[178:179], off
	v_lshl_add_u64 v[178:179], v[228:229], 0, s[6:7]
	s_mov_b32 m0, s35
	s_nop 0
	global_load_lds_dwordx4 v[178:179], off
	s_add_i32 s46, s46, 2
	s_add_u32 s20, s20, 0x100
	s_addc_u32 s21, s21, 0
	s_add_u32 s44, s44, 0x100
	s_addc_u32 s45, s45, 0
	s_cmp_gt_u32 s46, 13

.LBB0_1460:
	s_add_u32 s43, s20, 0x100
	s_addc_u32 s44, s21, 0
	s_mov_b32 s45, -2
	s_waitcnt lgkmcnt(0)
	ds_read_b128 v[144:147], v151
	ds_read_b128 v[156:159], v151 offset:1024
	ds_read_b128 v[160:163], v151 offset:2048
	ds_read_b128 v[164:167], v151 offset:3072
	ds_read_b128 v[168:171], v152
	ds_read_b128 v[172:175], v152 offset:1024
	ds_read_b128 v[176:179], v152 offset:2048
	ds_read_b128 v[182:185], v152 offset:3072
	s_add_u32 s20, s18, 0x100
	s_addc_u32 s21, s19, 0
	s_cmp_eq_u32 s45, 40
	s_cselect_b32 s25, s7, s21
	s_cselect_b32 s24, s6, s20
	s_cselect_b32 s23, s17, s44
	s_cselect_b32 s22, s16, s43
	v_lshl_add_u64 v[218:219], s[18:19], 0, v[136:137]
	s_add_i32 m0, s29, 0xc000
	ds_read_b128 v[186:189], v153
	ds_read_b128 v[190:193], v153 offset:1024
	ds_read_b128 v[194:197], v153 offset:2048
	ds_read_b128 v[198:201], v153 offset:3072
	ds_read_b128 v[202:205], v153 offset:4096
	ds_read_b128 v[206:209], v153 offset:5120
	ds_read_b128 v[210:213], v153 offset:6144
	ds_read_b128 v[214:217], v153 offset:7168
	global_load_lds_dwordx4 v[218:219], off
	v_lshl_add_u64 v[218:219], s[18:19], 0, v[138:139]
	s_add_i32 m0, s29, 0xe000
	s_nop 0
	global_load_lds_dwordx4 v[218:219], off
	s_waitcnt vmcnt(8)
	s_waitcnt lgkmcnt(0)
	s_barrier
	s_waitcnt lgkmcnt(0)
	v_mfma_f32_16x16x32_bf16 v[124:127], v[144:147], v[186:189], 0
	v_mfma_f32_16x16x32_bf16 v[120:123], v[160:163], v[186:189], 0
	v_mfma_f32_16x16x32_bf16 v[108:111], v[144:147], v[194:197], 0
	v_mfma_f32_16x16x32_bf16 v[104:107], v[160:163], v[194:197], 0
	v_mfma_f32_16x16x32_bf16 v[92:95], v[144:147], v[202:205], 0
	v_mfma_f32_16x16x32_bf16 v[88:91], v[160:163], v[202:205], 0
	v_mfma_f32_16x16x32_bf16 v[76:79], v[144:147], v[210:213], 0
	v_mfma_f32_16x16x32_bf16 v[72:75], v[160:163], v[210:213], 0
	v_mfma_f32_16x16x32_bf16 v[124:127], v[156:159], v[190:193], v[124:127]
	v_mfma_f32_16x16x32_bf16 v[120:123], v[164:167], v[190:193], v[120:123]
	v_mfma_f32_16x16x32_bf16 v[108:111], v[156:159], v[198:201], v[108:111]
	v_mfma_f32_16x16x32_bf16 v[104:107], v[164:167], v[198:201], v[104:107]
	v_mfma_f32_16x16x32_bf16 v[92:95], v[156:159], v[206:209], v[92:95]
	v_mfma_f32_16x16x32_bf16 v[88:91], v[164:167], v[206:209], v[88:91]
	v_mfma_f32_16x16x32_bf16 v[76:79], v[156:159], v[214:217], v[76:79]
	v_mfma_f32_16x16x32_bf16 v[72:75], v[164:167], v[214:217], v[72:75]
	v_mfma_f32_16x16x32_bf16 v[116:119], v[168:171], v[186:189], 0
	v_mfma_f32_16x16x32_bf16 v[112:115], v[176:179], v[186:189], 0
	v_mfma_f32_16x16x32_bf16 v[100:103], v[168:171], v[194:197], 0
	v_mfma_f32_16x16x32_bf16 v[96:99], v[176:179], v[194:197], 0
	v_mfma_f32_16x16x32_bf16 v[84:87], v[168:171], v[202:205], 0
	v_mfma_f32_16x16x32_bf16 v[80:83], v[176:179], v[202:205], 0
	v_mfma_f32_16x16x32_bf16 v[68:71], v[168:171], v[210:213], 0
	v_mfma_f32_16x16x32_bf16 v[64:67], v[176:179], v[210:213], 0
	v_mfma_f32_16x16x32_bf16 v[116:119], v[172:175], v[190:193], v[116:119]
	v_mfma_f32_16x16x32_bf16 v[112:115], v[182:185], v[190:193], v[112:115]
	v_mfma_f32_16x16x32_bf16 v[100:103], v[172:175], v[198:201], v[100:103]
	v_mfma_f32_16x16x32_bf16 v[96:99], v[182:185], v[198:201], v[96:99]
	v_mfma_f32_16x16x32_bf16 v[84:87], v[172:175], v[206:209], v[84:87]
	v_mfma_f32_16x16x32_bf16 v[80:83], v[182:185], v[206:209], v[80:83]
	s_setprio 3
	s_barrier
	v_mfma_f32_16x16x32_bf16 v[68:71], v[172:175], v[214:217], v[68:71]
	v_mfma_f32_16x16x32_bf16 v[64:67], v[182:185], v[214:217], v[64:67]
	s_setprio 0
	s_add_i32 s18, s37, s28
	v_lshl_add_u64 v[218:219], s[22:23], 0, v[130:131]
	s_mov_b32 m0, s18
	ds_read_b128 v[186:189], v153 offset:16384
	ds_read_b128 v[190:193], v153 offset:17408
	ds_read_b128 v[194:197], v153 offset:18432
	ds_read_b128 v[198:201], v153 offset:19456
	ds_read_b128 v[202:205], v153 offset:20480
	ds_read_b128 v[206:209], v153 offset:21504
	ds_read_b128 v[210:213], v153 offset:22528
	ds_read_b128 v[214:217], v153 offset:23552
	global_load_lds_dwordx4 v[218:219], off
	s_add_i32 m0, s18, 0x2000
	s_add_u32 s18, s22, 0xb0000
	v_lshl_add_u64 v[220:221], s[22:23], 0, v[134:135]
	s_addc_u32 s19, s23, 0
	s_add_i32 s46, s38, s28
	global_load_lds_dwordx4 v[220:221], off
	v_lshl_add_u64 v[222:223], s[18:19], 0, v[130:131]
	s_mov_b32 m0, s46
	global_load_lds_dwordx4 v[222:223], off
	v_lshl_add_u64 v[222:223], s[18:19], 0, v[134:135]
	s_add_i32 m0, s46, 0x2000
	s_nop 0
	global_load_lds_dwordx4 v[222:223], off
	s_waitcnt vmcnt(6)
	s_waitcnt lgkmcnt(0)
	s_barrier
	s_waitcnt lgkmcnt(0)
	v_mfma_f32_16x16x32_bf16 v[60:63], v[144:147], v[186:189], 0
	v_mfma_f32_16x16x32_bf16 v[56:59], v[160:163], v[186:189], 0
	v_mfma_f32_16x16x32_bf16 v[44:47], v[144:147], v[194:197], 0
	v_mfma_f32_16x16x32_bf16 v[40:43], v[160:163], v[194:197], 0
	v_mfma_f32_16x16x32_bf16 v[28:31], v[144:147], v[202:205], 0
	v_mfma_f32_16x16x32_bf16 v[24:27], v[160:163], v[202:205], 0
	v_mfma_f32_16x16x32_bf16 v[12:15], v[144:147], v[210:213], 0
	v_mfma_f32_16x16x32_bf16 v[8:11], v[160:163], v[210:213], 0
	v_mfma_f32_16x16x32_bf16 v[60:63], v[156:159], v[190:193], v[60:63]
	v_mfma_f32_16x16x32_bf16 v[56:59], v[164:167], v[190:193], v[56:59]
	v_mfma_f32_16x16x32_bf16 v[44:47], v[156:159], v[198:201], v[44:47]
	v_mfma_f32_16x16x32_bf16 v[40:43], v[164:167], v[198:201], v[40:43]
	v_mfma_f32_16x16x32_bf16 v[28:31], v[156:159], v[206:209], v[28:31]
	v_mfma_f32_16x16x32_bf16 v[24:27], v[164:167], v[206:209], v[24:27]
	v_mfma_f32_16x16x32_bf16 v[12:15], v[156:159], v[214:217], v[12:15]
	v_mfma_f32_16x16x32_bf16 v[8:11], v[164:167], v[214:217], v[8:11]
	v_mfma_f32_16x16x32_bf16 v[52:55], v[168:171], v[186:189], 0
	v_mfma_f32_16x16x32_bf16 v[48:51], v[176:179], v[186:189], 0
	v_mfma_f32_16x16x32_bf16 v[36:39], v[168:171], v[194:197], 0
	v_mfma_f32_16x16x32_bf16 v[32:35], v[176:179], v[194:197], 0
	v_mfma_f32_16x16x32_bf16 v[20:23], v[168:171], v[202:205], 0
	v_mfma_f32_16x16x32_bf16 v[16:19], v[176:179], v[202:205], 0
	v_mfma_f32_16x16x32_bf16 v[4:7], v[168:171], v[210:213], 0
	v_mfma_f32_16x16x32_bf16 v[0:3], v[176:179], v[210:213], 0
	v_mfma_f32_16x16x32_bf16 v[52:55], v[172:175], v[190:193], v[52:55]
	v_mfma_f32_16x16x32_bf16 v[48:51], v[182:185], v[190:193], v[48:51]
	v_mfma_f32_16x16x32_bf16 v[36:39], v[172:175], v[198:201], v[36:39]
	v_mfma_f32_16x16x32_bf16 v[32:35], v[182:185], v[198:201], v[32:35]
	v_mfma_f32_16x16x32_bf16 v[20:23], v[172:175], v[206:209], v[20:23]
	v_mfma_f32_16x16x32_bf16 v[16:19], v[182:185], v[206:209], v[16:19]
	s_setprio 3
	s_barrier
	v_mfma_f32_16x16x32_bf16 v[4:7], v[172:175], v[214:217], v[4:7]
	v_mfma_f32_16x16x32_bf16 v[0:3], v[182:185], v[214:217], v[0:3]
	s_setprio 0
	s_add_i32 s46, 0, 0x18000
	v_add_u32_e32 v155, s46, v149
	s_add_i32 s47, 0, 0x1c000
	ds_read_b128 v[144:147], v155
	ds_read_b128 v[156:159], v155 offset:1024
	ds_read_b128 v[160:163], v155 offset:2048
	ds_read_b128 v[164:167], v155 offset:3072
	v_add_u32_e32 v155, s47, v149
	ds_read_b128 v[168:171], v155
	ds_read_b128 v[172:175], v155 offset:1024
	ds_read_b128 v[176:179], v155 offset:2048
	ds_read_b128 v[182:185], v155 offset:3072
	s_add_u32 s18, s24, 0xb0000
	s_addc_u32 s19, s25, 0
	v_lshl_add_u64 v[222:223], s[24:25], 0, v[128:129]
	s_mov_b32 m0, s29
	v_lshl_add_u64 v[224:225], s[24:25], 0, v[132:133]
	global_load_lds_dwordx4 v[222:223], off
	s_mov_b32 m0, s30
	s_nop 0
	global_load_lds_dwordx4 v[224:225], off
	s_mov_b32 m0, s31
	v_lshl_add_u64 v[226:227], s[18:19], 0, v[128:129]
	ds_read_b128 v[186:189], v153 offset:32768
	ds_read_b128 v[190:193], v153 offset:33792
	ds_read_b128 v[194:197], v153 offset:34816
	ds_read_b128 v[198:201], v153 offset:35840
	ds_read_b128 v[202:205], v153 offset:36864
	ds_read_b128 v[206:209], v153 offset:37888
	ds_read_b128 v[210:213], v153 offset:38912
	ds_read_b128 v[214:217], v153 offset:39936
	global_load_lds_dwordx4 v[226:227], off
	v_lshl_add_u64 v[226:227], s[18:19], 0, v[132:133]
	s_mov_b32 m0, s33
	s_nop 0
	global_load_lds_dwordx4 v[226:227], off
	s_waitcnt vmcnt(8)
	s_waitcnt lgkmcnt(0)
	s_barrier
	s_waitcnt lgkmcnt(0)
	v_mfma_f32_16x16x32_bf16 v[124:127], v[144:147], v[186:189], v[124:127]
	v_mfma_f32_16x16x32_bf16 v[120:123], v[160:163], v[186:189], v[120:123]
	v_mfma_f32_16x16x32_bf16 v[108:111], v[144:147], v[194:197], v[108:111]
	v_mfma_f32_16x16x32_bf16 v[104:107], v[160:163], v[194:197], v[104:107]
	v_mfma_f32_16x16x32_bf16 v[92:95], v[144:147], v[202:205], v[92:95]
	v_mfma_f32_16x16x32_bf16 v[88:91], v[160:163], v[202:205], v[88:91]
	v_mfma_f32_16x16x32_bf16 v[76:79], v[144:147], v[210:213], v[76:79]
	v_mfma_f32_16x16x32_bf16 v[72:75], v[160:163], v[210:213], v[72:75]
	v_mfma_f32_16x16x32_bf16 v[124:127], v[156:159], v[190:193], v[124:127]
	v_mfma_f32_16x16x32_bf16 v[120:123], v[164:167], v[190:193], v[120:123]
	v_mfma_f32_16x16x32_bf16 v[108:111], v[156:159], v[198:201], v[108:111]
	v_mfma_f32_16x16x32_bf16 v[104:107], v[164:167], v[198:201], v[104:107]
	v_mfma_f32_16x16x32_bf16 v[92:95], v[156:159], v[206:209], v[92:95]
	v_mfma_f32_16x16x32_bf16 v[88:91], v[164:167], v[206:209], v[88:91]
	v_mfma_f32_16x16x32_bf16 v[76:79], v[156:159], v[214:217], v[76:79]
	v_mfma_f32_16x16x32_bf16 v[72:75], v[164:167], v[214:217], v[72:75]
	v_mfma_f32_16x16x32_bf16 v[116:119], v[168:171], v[186:189], v[116:119]
	v_mfma_f32_16x16x32_bf16 v[112:115], v[176:179], v[186:189], v[112:115]
	v_mfma_f32_16x16x32_bf16 v[100:103], v[168:171], v[194:197], v[100:103]
	v_mfma_f32_16x16x32_bf16 v[96:99], v[176:179], v[194:197], v[96:99]
	v_mfma_f32_16x16x32_bf16 v[84:87], v[168:171], v[202:205], v[84:87]
	v_mfma_f32_16x16x32_bf16 v[80:83], v[176:179], v[202:205], v[80:83]
	v_mfma_f32_16x16x32_bf16 v[68:71], v[168:171], v[210:213], v[68:71]
	v_mfma_f32_16x16x32_bf16 v[64:67], v[176:179], v[210:213], v[64:67]
	v_mfma_f32_16x16x32_bf16 v[116:119], v[172:175], v[190:193], v[116:119]
	v_mfma_f32_16x16x32_bf16 v[112:115], v[182:185], v[190:193], v[112:115]
	v_mfma_f32_16x16x32_bf16 v[100:103], v[172:175], v[198:201], v[100:103]
	v_mfma_f32_16x16x32_bf16 v[96:99], v[182:185], v[198:201], v[96:99]
	v_mfma_f32_16x16x32_bf16 v[84:87], v[172:175], v[206:209], v[84:87]
	v_mfma_f32_16x16x32_bf16 v[80:83], v[182:185], v[206:209], v[80:83]
	s_setprio 3
	s_barrier
	v_mfma_f32_16x16x32_bf16 v[68:71], v[172:175], v[214:217], v[68:71]
	v_mfma_f32_16x16x32_bf16 v[64:67], v[182:185], v[214:217], v[64:67]
	s_setprio 0
	s_add_i32 s18, s46, s28
	v_lshl_add_u64 v[218:219], v[218:219], 0, s[12:13]
	s_mov_b32 m0, s18
	ds_read_b128 v[186:189], v153 offset:49152
	ds_read_b128 v[190:193], v153 offset:50176
	ds_read_b128 v[194:197], v153 offset:51200
	ds_read_b128 v[198:201], v153 offset:52224
	ds_read_b128 v[202:205], v153 offset:53248
	ds_read_b128 v[206:209], v153 offset:54272
	ds_read_b128 v[210:213], v153 offset:55296
	ds_read_b128 v[214:217], v153 offset:56320
	global_load_lds_dwordx4 v[218:219], off
	s_add_i32 m0, s18, 0x2000
	s_add_u32 s18, s22, 0xb0080
	v_lshl_add_u64 v[218:219], v[220:221], 0, s[12:13]
	s_addc_u32 s19, s23, 0
	s_add_i32 s22, s47, s28
	global_load_lds_dwordx4 v[218:219], off
	v_lshl_add_u64 v[218:219], s[18:19], 0, v[130:131]
	s_mov_b32 m0, s22
	s_nop 0
	global_load_lds_dwordx4 v[218:219], off
	v_lshl_add_u64 v[218:219], s[18:19], 0, v[134:135]
	s_add_i32 m0, s22, 0x2000
	s_nop 0
	global_load_lds_dwordx4 v[218:219], off
	s_waitcnt vmcnt(6)
	s_waitcnt lgkmcnt(0)
	s_barrier
	s_waitcnt lgkmcnt(0)
	v_mfma_f32_16x16x32_bf16 v[60:63], v[144:147], v[186:189], v[60:63]
	v_mfma_f32_16x16x32_bf16 v[56:59], v[160:163], v[186:189], v[56:59]
	v_mfma_f32_16x16x32_bf16 v[44:47], v[144:147], v[194:197], v[44:47]
	v_mfma_f32_16x16x32_bf16 v[40:43], v[160:163], v[194:197], v[40:43]
	v_mfma_f32_16x16x32_bf16 v[28:31], v[144:147], v[202:205], v[28:31]
	v_mfma_f32_16x16x32_bf16 v[24:27], v[160:163], v[202:205], v[24:27]
	v_mfma_f32_16x16x32_bf16 v[12:15], v[144:147], v[210:213], v[12:15]
	v_mfma_f32_16x16x32_bf16 v[8:11], v[160:163], v[210:213], v[8:11]
	v_mfma_f32_16x16x32_bf16 v[60:63], v[156:159], v[190:193], v[60:63]
	v_mfma_f32_16x16x32_bf16 v[56:59], v[164:167], v[190:193], v[56:59]
	v_mfma_f32_16x16x32_bf16 v[44:47], v[156:159], v[198:201], v[44:47]
	v_mfma_f32_16x16x32_bf16 v[40:43], v[164:167], v[198:201], v[40:43]
	v_mfma_f32_16x16x32_bf16 v[28:31], v[156:159], v[206:209], v[28:31]
	v_mfma_f32_16x16x32_bf16 v[24:27], v[164:167], v[206:209], v[24:27]
	v_mfma_f32_16x16x32_bf16 v[12:15], v[156:159], v[214:217], v[12:15]
	v_mfma_f32_16x16x32_bf16 v[8:11], v[164:167], v[214:217], v[8:11]
	v_mfma_f32_16x16x32_bf16 v[52:55], v[168:171], v[186:189], v[52:55]
	v_mfma_f32_16x16x32_bf16 v[48:51], v[176:179], v[186:189], v[48:51]
	v_mfma_f32_16x16x32_bf16 v[36:39], v[168:171], v[194:197], v[36:39]
	v_mfma_f32_16x16x32_bf16 v[32:35], v[176:179], v[194:197], v[32:35]
	v_mfma_f32_16x16x32_bf16 v[20:23], v[168:171], v[202:205], v[20:23]
	v_mfma_f32_16x16x32_bf16 v[16:19], v[176:179], v[202:205], v[16:19]
	v_mfma_f32_16x16x32_bf16 v[4:7], v[168:171], v[210:213], v[4:7]
	v_mfma_f32_16x16x32_bf16 v[0:3], v[176:179], v[210:213], v[0:3]
	v_mfma_f32_16x16x32_bf16 v[52:55], v[172:175], v[190:193], v[52:55]
	v_mfma_f32_16x16x32_bf16 v[48:51], v[182:185], v[190:193], v[48:51]
	v_mfma_f32_16x16x32_bf16 v[36:39], v[172:175], v[198:201], v[36:39]
	v_mfma_f32_16x16x32_bf16 v[32:35], v[182:185], v[198:201], v[32:35]
	v_mfma_f32_16x16x32_bf16 v[20:23], v[172:175], v[206:209], v[20:23]
	v_mfma_f32_16x16x32_bf16 v[16:19], v[182:185], v[206:209], v[16:19]
	s_setprio 3
	s_barrier
	v_mfma_f32_16x16x32_bf16 v[4:7], v[172:175], v[214:217], v[4:7]
	v_mfma_f32_16x16x32_bf16 v[0:3], v[182:185], v[214:217], v[0:3]
	s_setprio 0
	v_lshl_add_u64 v[218:219], v[222:223], 0, s[12:13]
	s_mov_b32 m0, s35
	s_nop 0
	global_load_lds_dwordx4 v[218:219], off
	v_lshl_add_u64 v[218:219], v[224:225], 0, s[12:13]
	s_mov_b32 m0, s36
	s_nop 0
	global_load_lds_dwordx4 v[218:219], off
	s_add_i32 s45, s45, 2
	s_add_u32 s43, s43, 0x100
	s_addc_u32 s44, s44, 0
	s_cmp_gt_u32 s45, 41
	s_mov_b64 s[18:19], s[20:21]
